# attention softmax: fixed shift (negb) adds removed - shift-invariant softmax with bounded scores; in-place adds deleted, copy-adds turned into moves; plus K swizzle; on top of v12
# baseline (speedup 1.0000x reference)
; __device__ __forceinline__ void expA(f32x16& p0, const float negb) { p0 = p0 + negb; for (int r = 0; r < 16; ++r) p0[r] = __builtin_amdgcn_exp2f(p0[r]); }
; __device__ __forceinline__ int v_st(int k, int c) { const int kk = (k & ~0xC) | ((k & 4) << 1) | ((k & 8) >> 1); return ((kk >> 3) * 4 + (c >> 5)) * 512 + ((kk & 7) * 32 + (c & 31)) * 2; }
; __device__ __forceinline__ int v_rd_base(int lane) { return ((lane & 3) << 3) | (((lane >> 2) & 3) << 6) | (((lane >> 4) & 1) << 5) | (((lane >> 5) & 1) << 8); }
; #define SLOAD(i, k0) do { const unsigned a_ = (unsigned)(k0) * (unsigned)LDK + so0; sr_[i].vs0 = ld8(Kh + (a_ + 256u)); sr_[i].vs1 = ld8(Kh + (a_ + 32u * LDK + 256u)); \
;     sr_[i].ks0 = ld8(Kh + a_); sr_[i].ks1 = ld8(Kh + (a_ + 32u * LDK)); } while (0)
; #define SWRITE(b, i) do { *(bf16x8*)((char*)V_lds + (b) * SHM_V + vst0) = sr_[i].vs0;          \
;     *(bf16x8*)((char*)V_lds + (b) * SHM_V + vst1) = sr_[i].vs1; int kc = sc * 2;               \
;     *(bf16x8*)((char*)K_lds + (b) * SHM_K + KSWZ(sr, kc)) = sr_[i].ks0;                       \
;     *(bf16x8*)((char*)K_lds + (b) * SHM_K + KSWZ(32 + sr, kc)) = sr_[i].ks1; } while (0)
; __device__ __forceinline__ void attn_dense_body(const bf16* __restrict__ Qb, const bf16* __restrict__ Kh, const bf16* __restrict__ Vh,
;                                                 bf16* __restrict__ Ob, int seq, char* lds, const float negb) {
;     ...
;   const bf16* Qw = Qb + (long)(wid * QBLK + r32) * LDQ + hi * 8;
; #pragma unroll
;   for (int d0 = 0; d0 < 8; ++d0) qr[d0] = ld8(Qw + d0 * 16);
;   const int sr = tid >> 4, sc = (tid & 15) * 8, vst0 = v_st(sr, sc), vst1 = v_st(32 + sr, sc);
;   const int vb0 = (int)(uintptr_t)V_lds + v_rd_base(lane);
;   struct { bf16x8 vs0, vs1, ks0, ks1; } sr_[1];
;   const unsigned so0 = (unsigned)(sr * LDK + sc);
;     ...
;   f32x16 pA0, pA1, pB0, pB1; bf16x8 pa0, pa1, pa2, pa3; const int NT = seq / KVBLK;
;   constexpr int SE = 0, SO = 0;
;   SLOAD(SE, 0); asm volatile("s_waitcnt vmcnt(0)" ::: "memory"); SWRITE(0, SE); __syncthreads();
;   qkt(pA0, pA1, K_lds, qr, r32, hi); expA(pA0, negb);
.LBB0_284:
	s_mul_i32 s8, s35, s88
	s_add_i32 s8, s8, s2
	s_cmpk_gt_i32 s8, 0x4ff
	s_mov_b64 s[62:63], -1
	s_cbranch_scc1 .LBB0_283
	s_add_i32 s36, s8, 0xfffffc00
	s_cmpk_lt_i32 s8, 0x400
	s_cselect_b32 s36, s8, s36
	s_cselect_b32 s37, 8, 7
	s_ashr_i32 s37, s36, s37
	s_lshl_b32 s62, s37, 13
	s_addk_i32 s62, 0x2000
	s_lshl_b32 s63, s37, 12
	s_cmpk_lt_i32 s8, 0x400
	s_cselect_b32 s8, 31, 15
	s_cselect_b32 s64, 5, 4
	s_cselect_b32 s37, 0x80, 64
	s_cselect_b32 s80, s62, s63
	s_and_b32 s8, s36, s8
	s_lshr_b32 s36, s36, s64
	s_and_b32 s81, s36, 7
	s_mul_i32 s66, s80, 0xc00
	s_mul_hi_u32 s67, s80, 0xc00
	s_add_u32 s62, s20, s66
	s_addc_u32 s63, s21, s67
	s_lshl_b32 s36, s36, 6
	s_and_b32 s77, s36, 0x100
	s_add_u32 s62, s62, s77
	s_addc_u32 s63, s63, 0
	s_add_u32 s64, s62, 0x800
	s_addc_u32 s65, s63, 0
	s_lshl_b32 s8, s8, 8
	s_add_i32 s8, s80, s8
	s_mul_i32 s80, s8, 0xc00
	s_mul_hi_u32 s36, s8, 0xc00
	s_add_u32 s80, s20, s80
	s_addc_u32 s82, s21, s36
	s_lshl_b32 s36, s81, 7
	s_lshl_b32 s81, s81, 8
	s_add_u32 s80, s80, s81
	s_addc_u32 s81, s82, 0
	v_mov_b32_e32 v167, v149
	v_mov_b32_e32 v171, v149
	v_lshl_add_u64 v[0:1], s[80:81], 0, v[166:167]
	v_lshl_add_u64 v[24:25], s[62:63], 0, v[170:171]
	s_mov_b32 s80, 0x18000
	v_mov_b32_e32 v169, v149
	v_add_co_u32_e32 v12, vcc, s80, v24
	v_lshl_add_u64 v[0:1], v[0:1], 0, v[168:169]
	s_nop 0
	v_addc_co_u32_e32 v13, vcc, 0, v25, vcc
	global_load_dwordx4 v[140:143], v[0:1], off
	global_load_dwordx4 v[136:139], v[0:1], off offset:32
	global_load_dwordx4 v[132:135], v[0:1], off offset:64
	global_load_dwordx4 v[128:131], v[0:1], off offset:96
	global_load_dwordx4 v[124:127], v[0:1], off offset:128
	global_load_dwordx4 v[120:123], v[0:1], off offset:160
	global_load_dwordx4 v[116:119], v[0:1], off offset:192
	global_load_dwordx4 v[112:115], v[0:1], off offset:224
	s_mov_b32 s80, 0x30000
	global_load_dwordx4 v[0:3], v170, s[62:63] offset:2560
	global_load_dwordx4 v[4:7], v[12:13], off offset:2560
	global_load_dwordx4 v[8:11], v170, s[62:63] offset:2048
	s_nop 0
	global_load_dwordx4 v[12:15], v[12:13], off offset:2048
	s_waitcnt vmcnt(0)
	v_add_co_u32_e32 v26, vcc, s80, v24
	s_mov_b32 s80, 0x48000
	s_nop 0
	v_addc_co_u32_e32 v27, vcc, 0, v25, vcc
	v_add_co_u32_e32 v28, vcc, s80, v24
	s_or_b32 s66, s66, s77
	s_nop 0
	v_addc_co_u32_e32 v29, vcc, 0, v25, vcc
	v_mov_b32_e32 v167, 0
	v_lshl_add_u64 v[178:179], v[164:165], 0, s[66:67]
	s_mov_b32 s66, 2
	v_mov_b32_e32 v148, v193
	v_mov_b32_e32 v32, 0
	v_mov_b32_e32 v33, v167
	v_mov_b32_e32 v34, v167
	v_mov_b32_e32 v35, v167
	v_mov_b32_e32 v36, v167
	v_mov_b32_e32 v37, v167
	v_mov_b32_e32 v38, v167
	v_mov_b32_e32 v39, v167
	v_mov_b32_e32 v40, v167
	v_mov_b32_e32 v41, v167
	v_mov_b32_e32 v42, v167
	v_mov_b32_e32 v43, v167
	v_mov_b32_e32 v44, v167
	v_mov_b32_e32 v45, v167
	v_mov_b32_e32 v46, v167
	v_mov_b32_e32 v47, v167
	v_mov_b32_e32 v48, 0
	v_mov_b32_e32 v49, v167
	v_mov_b32_e32 v50, v167
	v_mov_b32_e32 v51, v167
	v_mov_b32_e32 v52, v167
	v_mov_b32_e32 v53, v167
	v_mov_b32_e32 v54, v167
	v_mov_b32_e32 v55, v167
	v_mov_b32_e32 v56, v167
	v_mov_b32_e32 v57, v167
	v_mov_b32_e32 v58, v167
	v_mov_b32_e32 v59, v167
	v_mov_b32_e32 v60, v167
	v_mov_b32_e32 v61, v167
	v_mov_b32_e32 v62, v167
	v_mov_b32_e32 v63, v167
	s_waitcnt vmcnt(3)
	ds_write_b128 v194, v[0:3]
	s_waitcnt vmcnt(2)
	ds_write_b128 v195, v[4:7]
	s_waitcnt vmcnt(1)
	ds_write_b128 v196, v[8:11] offset:32768
	s_waitcnt vmcnt(0)
	ds_write_b128 v197, v[12:15] offset:32768
	s_waitcnt lgkmcnt(0)
	s_barrier
	ds_read_b128 v[0:3], v198 offset:32768
	ds_read_b128 v[16:19], v198 offset:40960
	s_waitcnt lgkmcnt(1)
	v_mfma_f32_32x32x16_bf16 v[0:15], v[0:3], v[140:143], 0
	s_waitcnt lgkmcnt(0)
	v_mfma_f32_32x32x16_bf16 v[64:79], v[16:19], v[140:143], 0
	ds_read_b128 v[16:19], v199 offset:32768
	ds_read_b128 v[20:23], v199 offset:40960
	s_waitcnt lgkmcnt(1)
	v_mfma_f32_32x32x16_bf16 v[0:15], v[16:19], v[136:139], v[0:15]
	s_waitcnt lgkmcnt(0)
	v_mfma_f32_32x32x16_bf16 v[64:79], v[20:23], v[136:139], v[64:79]
	ds_read_b128 v[16:19], v200 offset:32768
	ds_read_b128 v[20:23], v200 offset:40960
	s_waitcnt lgkmcnt(1)
	v_mfma_f32_32x32x16_bf16 v[0:15], v[16:19], v[132:135], v[0:15]
	s_waitcnt lgkmcnt(0)
	v_mfma_f32_32x32x16_bf16 v[64:79], v[20:23], v[132:135], v[64:79]
	ds_read_b128 v[16:19], v201 offset:32768
	ds_read_b128 v[20:23], v201 offset:40960
	s_waitcnt lgkmcnt(1)
	v_mfma_f32_32x32x16_bf16 v[0:15], v[16:19], v[128:131], v[0:15]
	s_waitcnt lgkmcnt(0)
	v_mfma_f32_32x32x16_bf16 v[64:79], v[20:23], v[128:131], v[64:79]
	ds_read_b128 v[16:19], v202 offset:32768
	ds_read_b128 v[20:23], v202 offset:40960
	s_waitcnt lgkmcnt(1)
	v_mfma_f32_32x32x16_bf16 v[0:15], v[16:19], v[124:127], v[0:15]
	s_waitcnt lgkmcnt(0)
	v_mfma_f32_32x32x16_bf16 v[64:79], v[20:23], v[124:127], v[64:79]
	ds_read_b128 v[16:19], v203 offset:32768
	ds_read_b128 v[20:23], v203 offset:40960
	s_waitcnt lgkmcnt(1)
	v_mfma_f32_32x32x16_bf16 v[0:15], v[16:19], v[120:123], v[0:15]
	s_waitcnt lgkmcnt(0)
	v_mfma_f32_32x32x16_bf16 v[64:79], v[20:23], v[120:123], v[64:79]
	ds_read_b128 v[16:19], v204 offset:32768
	ds_read_b128 v[20:23], v204 offset:40960
	s_waitcnt lgkmcnt(1)
	v_mfma_f32_32x32x16_bf16 v[0:15], v[16:19], v[116:119], v[0:15]
	s_waitcnt lgkmcnt(0)
	v_mfma_f32_32x32x16_bf16 v[64:79], v[20:23], v[116:119], v[64:79]
	ds_read_b128 v[16:19], v205 offset:32768
	ds_read_b128 v[20:23], v205 offset:40960
	s_waitcnt lgkmcnt(1)
	v_mfma_f32_32x32x16_bf16 v[0:15], v[16:19], v[112:115], v[0:15]
	global_load_dwordx4 v[16:19], v[26:27], off offset:2560
	s_waitcnt lgkmcnt(0)
; #define SBAR() __builtin_amdgcn_sched_barrier(0)
; __device__ __forceinline__ void expA(f32x16& p0, const float negb) { p0 = p0 + negb; for (int r = 0; r < 16; ++r) p0[r] = __builtin_amdgcn_exp2f(p0[r]); }
; #define SLOAD(i, k0) do { const unsigned a_ = (unsigned)(k0) * (unsigned)LDK + so0; sr_[i].vs0 = ld8(Kh + (a_ + 256u)); sr_[i].vs1 = ld8(Kh + (a_ + 32u * LDK + 256u)); \
;     sr_[i].ks0 = ld8(Kh + a_); sr_[i].ks1 = ld8(Kh + (a_ + 32u * LDK)); } while (0)
; #define SWRITE(b, i) do { *(bf16x8*)((char*)V_lds + (b) * SHM_V + vst0) = sr_[i].vs0;          \
;     *(bf16x8*)((char*)V_lds + (b) * SHM_V + vst1) = sr_[i].vs1; int kc = sc * 2;               \
;     *(bf16x8*)((char*)K_lds + (b) * SHM_K + KSWZ(sr, kc)) = sr_[i].ks0;                       \
;     *(bf16x8*)((char*)K_lds + (b) * SHM_K + KSWZ(32 + sr, kc)) = sr_[i].ks1; } while (0)
; #define SWAIT() asm volatile("s_waitcnt vmcnt(0)" ::: "memory")
; __device__ __forceinline__ void finishSM(f32x16& p0, f32x16& p1, const float negb, float& l_reg, bf16x8& pa0, bf16x8& pa1, bf16x8& pa2, bf16x8& pa3) {
;   p1 = p1 + negb; for (int r = 0; r < 16; ++r) p1[r] = __builtin_amdgcn_exp2f(p1[r]);
;   float ps = 0; for (int r = 0; r < 16; ++r) ps += p0[r]; for (int r = 0; r < 16; ++r) ps += p1[r];
; __device__ __forceinline__ void attn_dense_body(const bf16* __restrict__ Qb, const bf16* __restrict__ Kh, const bf16* __restrict__ Vh,
;                                                 bf16* __restrict__ Ob, int seq, char* lds, const float negb) {
;     ...
;   SLOAD(SE, 0); asm volatile("s_waitcnt vmcnt(0)" ::: "memory"); SWRITE(0, SE); __syncthreads();
;   qkt(pA0, pA1, K_lds, qr, r32, hi); expA(pA0, negb);
;   SLOAD(SO, KVBLK);
;   SWAIT(); SWRITE(1, SO); __syncthreads();
;   for (int j = 1; j + 1 < NT; j += 2) {
;     SBAR(); qkt(pB0, pB1, (bf16*)((char*)K_lds + SHM_K), qr, r32, hi);
;     finishSM(pA0, pA1, negb, l_reg, pa0, pa1, pa2, pa3); SBAR();
	v_mfma_f32_32x32x16_bf16 v[64:79], v[20:23], v[112:115], v[64:79]
	global_load_dwordx4 v[20:23], v[28:29], off offset:2560
	s_nop 0
	global_load_dwordx4 v[24:27], v[26:27], off offset:2048
	s_nop 0
	global_load_dwordx4 v[28:31], v[28:29], off offset:2048
	s_nop 3
	v_exp_f32_e32 v212, v2
	v_exp_f32_e32 v214, v0
	v_exp_f32_e32 v216, v1
	v_exp_f32_e32 v215, v3
	v_exp_f32_e32 v211, v4
	v_exp_f32_e32 v213, v5
	v_exp_f32_e32 v209, v6
	v_exp_f32_e32 v210, v7
	v_exp_f32_e32 v206, v8
	v_exp_f32_e32 v208, v9
	v_exp_f32_e32 v177, v10
	v_exp_f32_e32 v207, v11
	v_exp_f32_e32 v171, v12
	v_exp_f32_e32 v175, v13
	v_exp_f32_e32 v169, v14
	v_exp_f32_e32 v173, v15
	s_waitcnt vmcnt(0)
	s_waitcnt vmcnt(3)
	ds_write_b128 v194, v[16:19] offset:16384
	s_waitcnt vmcnt(2)
	ds_write_b128 v195, v[20:23] offset:16384
	s_waitcnt vmcnt(1)
	ds_write_b128 v196, v[24:27] offset:49152
	s_waitcnt vmcnt(0)
	ds_write_b128 v197, v[28:31] offset:49152
	v_mov_b32_e32 v0, 0
	v_mov_b32_e32 v1, v167
	v_mov_b32_e32 v2, v167
	v_mov_b32_e32 v3, v167
	v_mov_b32_e32 v4, v167
	v_mov_b32_e32 v5, v167
	v_mov_b32_e32 v6, v167
	v_mov_b32_e32 v7, v167
	v_mov_b32_e32 v8, v167
	v_mov_b32_e32 v9, v167
	v_mov_b32_e32 v10, v167
	v_mov_b32_e32 v11, v167
	v_mov_b32_e32 v12, v167
	v_mov_b32_e32 v13, v167
	v_mov_b32_e32 v14, v167
	v_mov_b32_e32 v15, v167
	v_mov_b32_e32 v16, 0
	v_mov_b32_e32 v17, v167
	v_mov_b32_e32 v18, v167
	v_mov_b32_e32 v19, v167
	v_mov_b32_e32 v20, v167
	v_mov_b32_e32 v21, v167
	v_mov_b32_e32 v22, v167
	v_mov_b32_e32 v23, v167
	v_mov_b32_e32 v24, v167
	v_mov_b32_e32 v25, v167
	v_mov_b32_e32 v26, v167
	v_mov_b32_e32 v27, v167
	v_mov_b32_e32 v28, v167
	v_mov_b32_e32 v29, v167
	v_mov_b32_e32 v30, v167
	v_mov_b32_e32 v31, v167
	s_waitcnt lgkmcnt(0)
	s_barrier
.LBB0_286:
	ds_read_b128 v[80:83], v198 offset:49152
	ds_read_b128 v[84:87], v198 offset:57344
	ds_read_b128 v[218:221], v199 offset:49152
	ds_read_b128 v[222:225], v199 offset:57344
	s_waitcnt lgkmcnt(3)
	v_mfma_f32_32x32x16_bf16 v[96:111], v[80:83], v[140:143], 0
	v_exp_f32_e32 v188, v64
	v_add_f32_e32 v64, 0, v214
	v_add_f32_e32 v64, v216, v64
	v_add_f32_e32 v64, v212, v64
	v_add_f32_e32 v64, v215, v64
	v_add_f32_e32 v64, v211, v64
	v_add_f32_e32 v64, v213, v64
	s_waitcnt lgkmcnt(2)
	v_mfma_f32_32x32x16_bf16 v[80:95], v[84:87], v[140:143], 0
	v_add_f32_e32 v64, v209, v64
	v_add_f32_e32 v64, v210, v64
	v_add_f32_e32 v64, v206, v64
	v_add_f32_e32 v64, v208, v64
	v_add_f32_e32 v64, v177, v64
	v_add_f32_e32 v64, v207, v64
	v_add_f32_e32 v64, v171, v64
	s_waitcnt lgkmcnt(1)
	v_mfma_f32_32x32x16_bf16 v[96:111], v[218:221], v[136:139], v[96:111]
	v_exp_f32_e32 v189, v65
	v_add_f32_e32 v64, v175, v64
	v_exp_f32_e32 v217, v66
	v_add_f32_e32 v64, v169, v64
	v_add_f32_e32 v64, v173, v64
	v_add_f32_e32 v64, v188, v64
	s_waitcnt lgkmcnt(0)
	v_mfma_f32_32x32x16_bf16 v[80:95], v[222:225], v[136:139], v[80:95]
	ds_read_b128 v[218:221], v200 offset:49152
	ds_read_b128 v[222:225], v200 offset:57344
	v_add_f32_e32 v64, v189, v64
	v_add_f32_e32 v64, v217, v64
	s_waitcnt lgkmcnt(1)
	v_mfma_f32_32x32x16_bf16 v[96:111], v[218:221], v[132:135], v[96:111]
	v_exp_f32_e32 v226, v75
	v_exp_f32_e32 v227, v76
	v_exp_f32_e32 v228, v77
	v_exp_f32_e32 v229, v78
	v_exp_f32_e32 v79, v79
	s_waitcnt lgkmcnt(0)
	v_mfma_f32_32x32x16_bf16 v[80:95], v[222:225], v[132:135], v[80:95]
	ds_read_b128 v[218:221], v201 offset:49152
	ds_read_b128 v[222:225], v201 offset:57344
	s_waitcnt lgkmcnt(1)
	v_mfma_f32_32x32x16_bf16 v[96:111], v[218:221], v[128:131], v[96:111]
	s_waitcnt lgkmcnt(0)
	v_mfma_f32_32x32x16_bf16 v[80:95], v[222:225], v[128:131], v[80:95]
	ds_read_b128 v[218:221], v202 offset:49152
	ds_read_b128 v[222:225], v202 offset:57344
	s_waitcnt lgkmcnt(1)
	v_mfma_f32_32x32x16_bf16 v[96:111], v[218:221], v[124:127], v[96:111]
	s_waitcnt lgkmcnt(0)
	v_mfma_f32_32x32x16_bf16 v[80:95], v[222:225], v[124:127], v[80:95]
	ds_read_b128 v[218:221], v203 offset:49152
	ds_read_b128 v[222:225], v203 offset:57344
	s_waitcnt lgkmcnt(1)
	v_mfma_f32_32x32x16_bf16 v[96:111], v[218:221], v[120:123], v[96:111]
	s_waitcnt lgkmcnt(0)
	v_mfma_f32_32x32x16_bf16 v[80:95], v[222:225], v[120:123], v[80:95]
	ds_read_b128 v[218:221], v204 offset:49152
	ds_read_b128 v[222:225], v204 offset:57344
	s_waitcnt lgkmcnt(1)
	v_mfma_f32_32x32x16_bf16 v[96:111], v[218:221], v[116:119], v[96:111]
	s_waitcnt lgkmcnt(0)
	v_mfma_f32_32x32x16_bf16 v[80:95], v[222:225], v[116:119], v[80:95]
	ds_read_b128 v[218:221], v205 offset:49152
	ds_read_b128 v[222:225], v205 offset:57344
	s_waitcnt lgkmcnt(1)
	v_mfma_f32_32x32x16_bf16 v[96:111], v[218:221], v[112:115], v[96:111]
	v_exp_f32_e32 v218, v67
	v_exp_f32_e32 v219, v68
	v_exp_f32_e32 v220, v69
	v_exp_f32_e32 v221, v70
	v_add_f32_e32 v64, v218, v64
	v_add_f32_e32 v64, v219, v64
	v_add_f32_e32 v64, v220, v64
	s_waitcnt lgkmcnt(0)
; __device__ __forceinline__ void finishSM(f32x16& p0, f32x16& p1, const float negb, float& l_reg, bf16x8& pa0, bf16x8& pa1, bf16x8& pa2, bf16x8& pa3) {
;   p1 = p1 + negb; for (int r = 0; r < 16; ++r) p1[r] = __builtin_amdgcn_exp2f(p1[r]);
;   float ps = 0; for (int r = 0; r < 16; ++r) ps += p0[r]; for (int r = 0; r < 16; ++r) ps += p1[r];
;   l_reg += ps;
;     ...
;   PK4(p0, 0, pa0); PK4(p0, 8, pa1); PK4(p1, 0, pa2); PK4(p1, 8, pa3);
;     ...
; }
; __device__ __forceinline__ void qkt(f32x16& p0, f32x16& p1, const bf16* Ks, const bf16x8* qr, int r32, int hi) {
;   p0 = f32x16{}; p1 = f32x16{};
;   for (int d0 = 0; d0 < 8; ++d0) { int cb = (d0 * 16 + hi * 8) * 2;
;     bf16x8 b0 = *reinterpret_cast<const bf16x8*>((const char*)Ks + KSWZ(r32, cb));
;     bf16x8 b1 = *reinterpret_cast<const bf16x8*>((const char*)Ks + KSWZ(32 + r32, cb));
;     p0 = __builtin_amdgcn_mfma_f32_32x32x16_bf16(b0, qr[d0], p0, 0, 0, 0);
;     p1 = __builtin_amdgcn_mfma_f32_32x32x16_bf16(b1, qr[d0], p1, 0, 0, 0); }
; }
; __device__ __forceinline__ int v_st(int k, int c) { const int kk = (k & ~0xC) | ((k & 4) << 1) | ((k & 8) >> 1); return ((kk >> 3) * 4 + (c >> 5)) * 512 + ((kk & 7) * 32 + (c & 31)) * 2; }
; __device__ __forceinline__ int v_rd_base(int lane) { return ((lane & 3) << 3) | (((lane >> 2) & 3) << 6) | (((lane >> 4) & 1) << 5) | (((lane >> 5) & 1) << 8); }
; template <int OFF> __device__ __forceinline__ s16x4 tr_read(int vb) {
;   s16x4 r; asm volatile("ds_read_b64_tr_b16 %0, %1 offset:%2" : "=&v"(r) : "v"(vb), "i"(OFF) : "memory"); return r;
; }
; template <int D0> __device__ __forceinline__ void pv_one(f32x16& od, int vb, bf16x8 pa0, bf16x8 pa1, bf16x8 pa2, bf16x8 pa3) {
;   const s16x4 l0 = tr_read<v_rd_off(D0, 0, 0)>(vb), h0 = tr_read<v_rd_off(D0, 0, 1)>(vb), l1 = tr_read<v_rd_off(D0, 1, 0)>(vb), h1 = tr_read<v_rd_off(D0, 1, 1)>(vb);
;   const s16x4 l2 = tr_read<v_rd_off(D0, 2, 0)>(vb), h2 = tr_read<v_rd_off(D0, 2, 1)>(vb), l3 = tr_read<v_rd_off(D0, 3, 0)>(vb), h3 = tr_read<v_rd_off(D0, 3, 1)>(vb);
;   asm volatile("s_waitcnt lgkmcnt(0)" ::: "memory"); SBAR();
;     ...
;   od = __builtin_amdgcn_mfma_f32_32x32x16_bf16(pa0, PK(l0, h0), od, 0, 0, 0);
;   od = __builtin_amdgcn_mfma_f32_32x32x16_bf16(pa1, PK(l1, h1), od, 0, 0, 0);
;   od = __builtin_amdgcn_mfma_f32_32x32x16_bf16(pa2, PK(l2, h2), od, 0, 0, 0);
;   od = __builtin_amdgcn_mfma_f32_32x32x16_bf16(pa3, PK(l3, h3), od, 0, 0, 0);
;     ...
; }
	v_mfma_f32_32x32x16_bf16 v[80:95], v[222:225], v[112:115], v[80:95]
	v_exp_f32_e32 v222, v71
	v_exp_f32_e32 v223, v72
	v_exp_f32_e32 v224, v73
	v_exp_f32_e32 v225, v74
	v_add_f32_e32 v64, v221, v64
	v_add_f32_e32 v64, v222, v64
	v_add_f32_e32 v64, v223, v64
	v_add_f32_e32 v64, v224, v64
	v_add_f32_e32 v64, v225, v64
	v_add_f32_e32 v64, v226, v64
	v_add_f32_e32 v64, v227, v64
	v_add_f32_e32 v64, v228, v64
	v_add_f32_e32 v64, v229, v64
	v_add_f32_e32 v64, v79, v64
	v_add_f32_e32 v167, v167, v64
	v_cvt_pk_bf16_f32 v64, v214, v216
	v_cvt_pk_bf16_f32 v65, v212, v215
	v_cvt_pk_bf16_f32 v66, v211, v213
	v_cvt_pk_bf16_f32 v67, v209, v210
	v_cvt_pk_bf16_f32 v68, v206, v208
	v_cvt_pk_bf16_f32 v69, v177, v207
	v_cvt_pk_bf16_f32 v70, v171, v175
	v_cvt_pk_bf16_f32 v71, v169, v173
	v_cvt_pk_bf16_f32 v72, v188, v189
	v_cvt_pk_bf16_f32 v73, v217, v218
	v_cvt_pk_bf16_f32 v74, v219, v220
	v_cvt_pk_bf16_f32 v75, v221, v222
	v_cvt_pk_bf16_f32 v76, v223, v224
	v_cvt_pk_bf16_f32 v77, v225, v226
	v_cvt_pk_bf16_f32 v78, v227, v228
	v_cvt_pk_bf16_f32 v79, v229, v79
	s_nop 0
	v_permlane32_swap_b32_e32 v64, v66
	v_permlane32_swap_b32_e32 v65, v67
	v_permlane32_swap_b32_e32 v68, v70
	v_permlane32_swap_b32_e32 v69, v71
	v_permlane32_swap_b32_e32 v72, v74
	v_permlane32_swap_b32_e32 v73, v75
	v_permlane32_swap_b32_e32 v76, v78
	v_permlane32_swap_b32_e32 v77, v79
	s_mov_b32 s67, 0xfffe8000
	v_add_co_u32_e32 v210, vcc, s67, v178
	s_nop 1
	v_addc_co_u32_e32 v211, vcc, -1, v179, vcc
	global_load_dwordx4 v[206:209], v[210:211], off
	s_nop 0
	global_load_dwordx4 v[210:213], v[210:211], off offset:-512
	s_nop 0
	global_load_dwordx4 v[214:217], v[178:179], off
	global_load_dwordx4 v[218:221], v[178:179], off offset:-512
	ds_read_b64_tr_b16 v[222:223], v181 offset:0
	ds_read_b64_tr_b16 v[224:225], v181 offset:0x800
	ds_read_b64_tr_b16 v[226:227], v181 offset:0x1000
	ds_read_b64_tr_b16 v[228:229], v181 offset:0x1800
	ds_read_b64_tr_b16 v[230:231], v181 offset:0x2000
	ds_read_b64_tr_b16 v[232:233], v181 offset:0x2800
	ds_read_b64_tr_b16 v[234:235], v181 offset:0x3000
	ds_read_b64_tr_b16 v[236:237], v181 offset:0x3800
	s_waitcnt lgkmcnt(0)
	s_nop 0
	v_mfma_f32_32x32x16_bf16 v[0:15], v[64:67], v[222:225], v[0:15]
	ds_read_b64_tr_b16 v[222:223], v181 offset:0x200
	ds_read_b64_tr_b16 v[224:225], v181 offset:0xa00
	v_mfma_f32_32x32x16_bf16 v[0:15], v[68:71], v[226:229], v[0:15]
	ds_read_b64_tr_b16 v[226:227], v181 offset:0x1200
	ds_read_b64_tr_b16 v[228:229], v181 offset:0x1a00
	v_mfma_f32_32x32x16_bf16 v[0:15], v[72:75], v[230:233], v[0:15]
	ds_read_b64_tr_b16 v[230:231], v181 offset:0x2200
	ds_read_b64_tr_b16 v[232:233], v181 offset:0x2a00
	ds_read_b64_tr_b16 v[238:239], v181 offset:0x3200
	ds_read_b64_tr_b16 v[240:241], v181 offset:0x3a00
	s_waitcnt lgkmcnt(0)
	v_mfma_f32_32x32x16_bf16 v[0:15], v[76:79], v[234:237], v[0:15]
	v_mfma_f32_32x32x16_bf16 v[16:31], v[64:67], v[222:225], v[16:31]
	ds_read_b64_tr_b16 v[222:223], v181 offset:0x400
	ds_read_b64_tr_b16 v[224:225], v181 offset:0xc00
	v_mfma_f32_32x32x16_bf16 v[16:31], v[68:71], v[226:229], v[16:31]
	ds_read_b64_tr_b16 v[226:227], v181 offset:0x1400
	ds_read_b64_tr_b16 v[228:229], v181 offset:0x1c00
	v_mfma_f32_32x32x16_bf16 v[16:31], v[72:75], v[230:233], v[16:31]
	ds_read_b64_tr_b16 v[230:231], v181 offset:0x2400
	ds_read_b64_tr_b16 v[232:233], v181 offset:0x2c00
	ds_read_b64_tr_b16 v[234:235], v181 offset:0x3400
	ds_read_b64_tr_b16 v[236:237], v181 offset:0x3c00
	s_waitcnt lgkmcnt(0)
	v_mfma_f32_32x32x16_bf16 v[16:31], v[76:79], v[238:241], v[16:31]
	v_mfma_f32_32x32x16_bf16 v[32:47], v[64:67], v[222:225], v[32:47]
	ds_read_b64_tr_b16 v[222:223], v181 offset:0x600
	ds_read_b64_tr_b16 v[224:225], v181 offset:0xe00
	v_mfma_f32_32x32x16_bf16 v[32:47], v[68:71], v[226:229], v[32:47]
	ds_read_b64_tr_b16 v[226:227], v181 offset:0x1600
	ds_read_b64_tr_b16 v[228:229], v181 offset:0x1e00
	v_mfma_f32_32x32x16_bf16 v[32:47], v[72:75], v[230:233], v[32:47]
	ds_read_b64_tr_b16 v[230:231], v181 offset:0x2600
	ds_read_b64_tr_b16 v[232:233], v181 offset:0x2e00
	ds_read_b64_tr_b16 v[238:239], v181 offset:0x3600
	ds_read_b64_tr_b16 v[240:241], v181 offset:0x3e00
	s_waitcnt lgkmcnt(0)
	v_mfma_f32_32x32x16_bf16 v[32:47], v[76:79], v[234:237], v[32:47]
	v_mfma_f32_32x32x16_bf16 v[48:63], v[64:67], v[222:225], v[48:63]
	v_mfma_f32_32x32x16_bf16 v[48:63], v[68:71], v[226:229], v[48:63]
	v_mfma_f32_32x32x16_bf16 v[48:63], v[72:75], v[230:233], v[48:63]
	v_mfma_f32_32x32x16_bf16 v[48:63], v[76:79], v[238:241], v[48:63]
	v_mov_b64 v[74:75], v[100:101]
	v_mov_b64 v[76:77], v[98:99]
	v_mov_b64 v[78:79], v[96:97]
	v_exp_f32_e32 v173, v76
	v_exp_f32_e32 v169, v78
	v_exp_f32_e32 v171, v79
	v_exp_f32_e32 v175, v77
	v_exp_f32_e32 v177, v74
	v_mov_b64 v[64:65], v[110:111]
	v_mov_b64 v[66:67], v[108:109]
	v_mov_b64 v[68:69], v[106:107]
	v_mov_b64 v[70:71], v[104:105]
	v_mov_b64 v[72:73], v[102:103]
	v_exp_f32_e32 v188, v75
	v_exp_f32_e32 v189, v72
	v_exp_f32_e32 v222, v73
	v_exp_f32_e32 v223, v70
	v_exp_f32_e32 v224, v71
	v_exp_f32_e32 v225, v68
	v_exp_f32_e32 v226, v69
	v_exp_f32_e32 v227, v66
	v_exp_f32_e32 v228, v67
	v_exp_f32_e32 v229, v64
	v_exp_f32_e32 v230, v65
	s_barrier
	s_waitcnt vmcnt(0)
	s_waitcnt vmcnt(3)
	ds_write_b128 v194, v[206:209]
	s_waitcnt vmcnt(1)
	ds_write_b128 v195, v[214:217]
	ds_write_b128 v196, v[210:213] offset:32768
	s_waitcnt vmcnt(0)
	ds_write_b128 v197, v[218:221] offset:32768
	s_waitcnt lgkmcnt(0)
	s_barrier
; #define SBAR() __builtin_amdgcn_sched_barrier(0)
; __device__ __forceinline__ void expA(f32x16& p0, const float negb) { p0 = p0 + negb; for (int r = 0; r < 16; ++r) p0[r] = __builtin_amdgcn_exp2f(p0[r]); }
; #define SLOAD(i, k0) do { const unsigned a_ = (unsigned)(k0) * (unsigned)LDK + so0; sr_[i].vs0 = ld8(Kh + (a_ + 256u)); sr_[i].vs1 = ld8(Kh + (a_ + 32u * LDK + 256u)); \
;     sr_[i].ks0 = ld8(Kh + a_); sr_[i].ks1 = ld8(Kh + (a_ + 32u * LDK)); } while (0)
; __device__ __forceinline__ void finishSM(f32x16& p0, f32x16& p1, const float negb, float& l_reg, bf16x8& pa0, bf16x8& pa1, bf16x8& pa2, bf16x8& pa3) {
;   p1 = p1 + negb; for (int r = 0; r < 16; ++r) p1[r] = __builtin_amdgcn_exp2f(p1[r]);
;   float ps = 0; for (int r = 0; r < 16; ++r) ps += p0[r]; for (int r = 0; r < 16; ++r) ps += p1[r];
;   l_reg += ps;
;     ...
;   PK4(p0, 0, pa0); PK4(p0, 8, pa1); PK4(p1, 0, pa2); PK4(p1, 8, pa3);
;     ...
; }
; __device__ __forceinline__ void qkt(f32x16& p0, f32x16& p1, const bf16* Ks, const bf16x8* qr, int r32, int hi) {
;   p0 = f32x16{}; p1 = f32x16{};
;   for (int d0 = 0; d0 < 8; ++d0) { int cb = (d0 * 16 + hi * 8) * 2;
;     bf16x8 b0 = *reinterpret_cast<const bf16x8*>((const char*)Ks + KSWZ(r32, cb));
;     bf16x8 b1 = *reinterpret_cast<const bf16x8*>((const char*)Ks + KSWZ(32 + r32, cb));
;     p0 = __builtin_amdgcn_mfma_f32_32x32x16_bf16(b0, qr[d0], p0, 0, 0, 0);
;     p1 = __builtin_amdgcn_mfma_f32_32x32x16_bf16(b1, qr[d0], p1, 0, 0, 0); }
; __device__ __forceinline__ void attn_dense_body(const bf16* __restrict__ Qb, const bf16* __restrict__ Kh, const bf16* __restrict__ Vh,
;                                                 bf16* __restrict__ Ob, int seq, char* lds, const float negb) {
;     ...
;     SBAR(); qkt(pA0, pA1, K_lds, qr, r32, hi);
;     finishSM(pB0, pB1, negb, l_reg, pa0, pa1, pa2, pa3); SBAR();
;     SLOAD(SE, (j + 2) * KVBLK); SBAR();
;     pv_d0(o, vb0 + (int)SHM_V, pa0, pa1, pa2, pa3); SBAR(); expA(pA0, negb); SBAR();
	ds_read_b128 v[64:67], v198 offset:32768
	ds_read_b128 v[68:71], v198 offset:40960
	ds_read_b128 v[206:209], v199 offset:32768
	ds_read_b128 v[210:213], v199 offset:40960
	s_waitcnt lgkmcnt(3)
	v_mfma_f32_32x32x16_bf16 v[96:111], v[64:67], v[140:143], 0
	v_exp_f32_e32 v214, v88
	v_exp_f32_e32 v215, v89
	v_exp_f32_e32 v216, v90
	s_waitcnt lgkmcnt(2)
	v_mfma_f32_32x32x16_bf16 v[64:79], v[68:71], v[140:143], 0
	v_exp_f32_e32 v217, v91
	v_exp_f32_e32 v218, v92
	v_exp_f32_e32 v219, v93
	v_exp_f32_e32 v220, v94
	v_exp_f32_e32 v95, v95
	s_waitcnt lgkmcnt(1)
	v_mfma_f32_32x32x16_bf16 v[96:111], v[206:209], v[136:139], v[96:111]
	s_waitcnt lgkmcnt(0)
	v_mfma_f32_32x32x16_bf16 v[64:79], v[210:213], v[136:139], v[64:79]
	ds_read_b128 v[206:209], v200 offset:32768
	ds_read_b128 v[210:213], v200 offset:40960
	s_waitcnt lgkmcnt(1)
	v_mfma_f32_32x32x16_bf16 v[96:111], v[206:209], v[132:135], v[96:111]
	s_waitcnt lgkmcnt(0)
	v_mfma_f32_32x32x16_bf16 v[64:79], v[210:213], v[132:135], v[64:79]
	ds_read_b128 v[206:209], v201 offset:32768
	ds_read_b128 v[210:213], v201 offset:40960
	s_waitcnt lgkmcnt(1)
	v_mfma_f32_32x32x16_bf16 v[96:111], v[206:209], v[128:131], v[96:111]
	s_waitcnt lgkmcnt(0)
	v_mfma_f32_32x32x16_bf16 v[64:79], v[210:213], v[128:131], v[64:79]
	ds_read_b128 v[206:209], v202 offset:32768
	ds_read_b128 v[210:213], v202 offset:40960
	s_waitcnt lgkmcnt(1)
	v_mfma_f32_32x32x16_bf16 v[96:111], v[206:209], v[124:127], v[96:111]
	s_waitcnt lgkmcnt(0)
	v_mfma_f32_32x32x16_bf16 v[64:79], v[210:213], v[124:127], v[64:79]
	ds_read_b128 v[206:209], v203 offset:32768
	ds_read_b128 v[210:213], v203 offset:40960
	s_waitcnt lgkmcnt(1)
	v_mfma_f32_32x32x16_bf16 v[96:111], v[206:209], v[120:123], v[96:111]
	s_waitcnt lgkmcnt(0)
	v_mfma_f32_32x32x16_bf16 v[64:79], v[210:213], v[120:123], v[64:79]
	ds_read_b128 v[206:209], v204 offset:32768
	ds_read_b128 v[210:213], v204 offset:40960
	s_waitcnt lgkmcnt(1)
	v_mfma_f32_32x32x16_bf16 v[96:111], v[206:209], v[116:119], v[96:111]
	s_waitcnt lgkmcnt(0)
	v_mfma_f32_32x32x16_bf16 v[64:79], v[210:213], v[116:119], v[64:79]
	ds_read_b128 v[206:209], v205 offset:32768
	ds_read_b128 v[210:213], v205 offset:40960
	s_waitcnt lgkmcnt(1)
	v_mfma_f32_32x32x16_bf16 v[96:111], v[206:209], v[112:115], v[96:111]
	v_exp_f32_e32 v206, v80
	v_add_f32_e32 v80, 0, v169
	v_add_f32_e32 v80, v171, v80
	v_add_f32_e32 v80, v173, v80
	v_add_f32_e32 v80, v175, v80
	v_add_f32_e32 v80, v177, v80
	v_add_f32_e32 v80, v188, v80
	v_add_f32_e32 v80, v189, v80
	v_add_f32_e32 v80, v222, v80
	v_add_f32_e32 v80, v223, v80
	v_add_f32_e32 v80, v224, v80
	v_add_f32_e32 v80, v225, v80
	v_add_f32_e32 v80, v226, v80
	v_add_f32_e32 v80, v227, v80
	v_exp_f32_e32 v207, v81
	v_add_f32_e32 v80, v228, v80
	v_exp_f32_e32 v208, v82
	v_add_f32_e32 v80, v229, v80
	v_exp_f32_e32 v209, v83
	v_add_f32_e32 v80, v230, v80
	s_waitcnt lgkmcnt(0)
	v_mfma_f32_32x32x16_bf16 v[64:79], v[210:213], v[112:115], v[64:79]
	v_exp_f32_e32 v210, v84
	v_add_f32_e32 v80, v206, v80
	v_exp_f32_e32 v211, v85
	v_add_f32_e32 v80, v207, v80
	v_exp_f32_e32 v212, v86
	v_add_f32_e32 v80, v208, v80
	v_exp_f32_e32 v213, v87
	v_add_f32_e32 v80, v209, v80
	v_add_f32_e32 v80, v210, v80
	v_add_f32_e32 v80, v211, v80
	v_add_f32_e32 v80, v212, v80
	v_add_f32_e32 v80, v213, v80
	v_add_f32_e32 v80, v214, v80
	v_add_f32_e32 v80, v215, v80
	v_add_f32_e32 v80, v216, v80
	v_add_f32_e32 v80, v217, v80
	v_add_f32_e32 v80, v218, v80
	v_add_f32_e32 v80, v219, v80
	v_add_f32_e32 v80, v220, v80
	v_add_f32_e32 v80, v95, v80
	v_add_f32_e32 v167, v167, v80
	v_cvt_pk_bf16_f32 v80, v169, v171
	v_cvt_pk_bf16_f32 v81, v173, v175
	v_cvt_pk_bf16_f32 v82, v177, v188
	v_cvt_pk_bf16_f32 v83, v189, v222
	v_cvt_pk_bf16_f32 v84, v223, v224
	v_cvt_pk_bf16_f32 v85, v225, v226
	v_cvt_pk_bf16_f32 v86, v227, v228
	v_cvt_pk_bf16_f32 v87, v229, v230
	v_cvt_pk_bf16_f32 v88, v206, v207
	v_cvt_pk_bf16_f32 v89, v208, v209
	v_cvt_pk_bf16_f32 v90, v210, v211
	v_cvt_pk_bf16_f32 v91, v212, v213
	v_cvt_pk_bf16_f32 v92, v214, v215
	v_cvt_pk_bf16_f32 v93, v216, v217
	v_cvt_pk_bf16_f32 v94, v218, v219
	v_cvt_pk_bf16_f32 v95, v220, v95
	s_nop 0
	v_permlane32_swap_b32_e32 v80, v82
	v_permlane32_swap_b32_e32 v81, v83
	v_permlane32_swap_b32_e32 v84, v86
	v_permlane32_swap_b32_e32 v85, v87
	v_permlane32_swap_b32_e32 v88, v90
	v_permlane32_swap_b32_e32 v89, v91
	v_permlane32_swap_b32_e32 v92, v94
	v_permlane32_swap_b32_e32 v93, v95
	v_add_u32_e32 v210, 0xc100, v148
	v_mov_b32_e32 v211, v149
	v_lshl_add_u64 v[206:207], v[148:149], 1, s[62:63]
	v_add_u32_e32 v208, 0xc000, v148
	v_lshl_add_u64 v[210:211], v[210:211], 1, s[64:65]
	v_mov_b32_e32 v209, v149
	global_load_dwordx4 v[218:221], v[206:207], off offset:2560
	global_load_dwordx4 v[222:225], v[206:207], off offset:2048
	v_lshl_add_u64 v[206:207], v[208:209], 1, s[64:65]
	global_load_dwordx4 v[226:229], v[210:211], off
	global_load_dwordx4 v[230:233], v[206:207], off
	ds_read_b64_tr_b16 v[206:207], v191 offset:0
	ds_read_b64_tr_b16 v[208:209], v191 offset:0x800
	ds_read_b64_tr_b16 v[210:211], v191 offset:0x1000
	ds_read_b64_tr_b16 v[212:213], v191 offset:0x1800
	ds_read_b64_tr_b16 v[214:215], v191 offset:0x2000
	ds_read_b64_tr_b16 v[216:217], v191 offset:0x2800
	ds_read_b64_tr_b16 v[234:235], v191 offset:0x3000
	ds_read_b64_tr_b16 v[236:237], v191 offset:0x3800
	s_waitcnt lgkmcnt(0)
	s_nop 0
	v_mfma_f32_32x32x16_bf16 v[0:15], v[80:83], v[206:209], v[0:15]
	ds_read_b64_tr_b16 v[206:207], v191 offset:0x200
	ds_read_b64_tr_b16 v[208:209], v191 offset:0xa00
	v_mfma_f32_32x32x16_bf16 v[0:15], v[84:87], v[210:213], v[0:15]
	ds_read_b64_tr_b16 v[210:211], v191 offset:0x1200
	ds_read_b64_tr_b16 v[212:213], v191 offset:0x1a00
	v_mfma_f32_32x32x16_bf16 v[0:15], v[88:91], v[214:217], v[0:15]
	ds_read_b64_tr_b16 v[214:215], v191 offset:0x2200
	ds_read_b64_tr_b16 v[216:217], v191 offset:0x2a00
	ds_read_b64_tr_b16 v[238:239], v191 offset:0x3200
	ds_read_b64_tr_b16 v[240:241], v191 offset:0x3a00
	s_waitcnt lgkmcnt(0)
; #define SBAR() __builtin_amdgcn_sched_barrier(0)
; __device__ __forceinline__ void expA(f32x16& p0, const float negb) { p0 = p0 + negb; for (int r = 0; r < 16; ++r) p0[r] = __builtin_amdgcn_exp2f(p0[r]); }
; #define SWRITE(b, i) do { *(bf16x8*)((char*)V_lds + (b) * SHM_V + vst0) = sr_[i].vs0;          \
;     *(bf16x8*)((char*)V_lds + (b) * SHM_V + vst1) = sr_[i].vs1; int kc = sc * 2;               \
;     *(bf16x8*)((char*)K_lds + (b) * SHM_K + KSWZ(sr, kc)) = sr_[i].ks0;                       \
;     *(bf16x8*)((char*)K_lds + (b) * SHM_K + KSWZ(32 + sr, kc)) = sr_[i].ks1; } while (0)
; #define SWAIT() asm volatile("s_waitcnt vmcnt(0)" ::: "memory")
; template <int D0> __device__ __forceinline__ void pv_one(f32x16& od, int vb, bf16x8 pa0, bf16x8 pa1, bf16x8 pa2, bf16x8 pa3) {
;   const s16x4 l0 = tr_read<v_rd_off(D0, 0, 0)>(vb), h0 = tr_read<v_rd_off(D0, 0, 1)>(vb), l1 = tr_read<v_rd_off(D0, 1, 0)>(vb), h1 = tr_read<v_rd_off(D0, 1, 1)>(vb);
;   const s16x4 l2 = tr_read<v_rd_off(D0, 2, 0)>(vb), h2 = tr_read<v_rd_off(D0, 2, 1)>(vb), l3 = tr_read<v_rd_off(D0, 3, 0)>(vb), h3 = tr_read<v_rd_off(D0, 3, 1)>(vb);
;   asm volatile("s_waitcnt lgkmcnt(0)" ::: "memory"); SBAR();
;     ...
;   od = __builtin_amdgcn_mfma_f32_32x32x16_bf16(pa0, PK(l0, h0), od, 0, 0, 0);
;   od = __builtin_amdgcn_mfma_f32_32x32x16_bf16(pa1, PK(l1, h1), od, 0, 0, 0);
;   od = __builtin_amdgcn_mfma_f32_32x32x16_bf16(pa2, PK(l2, h2), od, 0, 0, 0);
;   od = __builtin_amdgcn_mfma_f32_32x32x16_bf16(pa3, PK(l3, h3), od, 0, 0, 0);
;     ...
; }
; __device__ __forceinline__ void pv_d0(f32x16* o, int vb, bf16x8 pa0, bf16x8 pa1, bf16x8 pa2, bf16x8 pa3) {
;   pv_one<0>(o[0], vb, pa0, pa1, pa2, pa3); pv_one<1>(o[1], vb, pa0, pa1, pa2, pa3); pv_one<2>(o[2], vb, pa0, pa1, pa2, pa3); pv_one<3>(o[3], vb, pa0, pa1, pa2, pa3);
; __device__ __forceinline__ void attn_dense_body(const bf16* __restrict__ Qb, const bf16* __restrict__ Kh, const bf16* __restrict__ Vh,
;                                                 bf16* __restrict__ Ob, int seq, char* lds, const float negb) {
;     ...
;     pv_d0(o, vb0 + (int)SHM_V, pa0, pa1, pa2, pa3); SBAR(); expA(pA0, negb); SBAR();
;     __syncthreads(); SWAIT(); SWRITE(1, SO); SBAR();
;     __syncthreads();
;   }
;   SBAR(); qkt(pB0, pB1, (bf16*)((char*)K_lds + SHM_K), qr, r32, hi);
;   finishSM(pA0, pA1, negb, l_reg, pa0, pa1, pa2, pa3); SBAR();
	v_mfma_f32_32x32x16_bf16 v[0:15], v[92:95], v[234:237], v[0:15]
	v_mfma_f32_32x32x16_bf16 v[16:31], v[80:83], v[206:209], v[16:31]
	ds_read_b64_tr_b16 v[206:207], v191 offset:0x400
	ds_read_b64_tr_b16 v[208:209], v191 offset:0xc00
	v_mfma_f32_32x32x16_bf16 v[16:31], v[84:87], v[210:213], v[16:31]
	ds_read_b64_tr_b16 v[210:211], v191 offset:0x1400
	ds_read_b64_tr_b16 v[212:213], v191 offset:0x1c00
	v_mfma_f32_32x32x16_bf16 v[16:31], v[88:91], v[214:217], v[16:31]
	ds_read_b64_tr_b16 v[214:215], v191 offset:0x2400
	ds_read_b64_tr_b16 v[216:217], v191 offset:0x2c00
	ds_read_b64_tr_b16 v[234:235], v191 offset:0x3400
	ds_read_b64_tr_b16 v[236:237], v191 offset:0x3c00
	s_waitcnt lgkmcnt(0)
	v_mfma_f32_32x32x16_bf16 v[16:31], v[92:95], v[238:241], v[16:31]
	v_mfma_f32_32x32x16_bf16 v[32:47], v[80:83], v[206:209], v[32:47]
	ds_read_b64_tr_b16 v[206:207], v191 offset:0x600
	ds_read_b64_tr_b16 v[208:209], v191 offset:0xe00
	v_mfma_f32_32x32x16_bf16 v[32:47], v[84:87], v[210:213], v[32:47]
	ds_read_b64_tr_b16 v[210:211], v191 offset:0x1600
	ds_read_b64_tr_b16 v[212:213], v191 offset:0x1e00
	v_mfma_f32_32x32x16_bf16 v[32:47], v[88:91], v[214:217], v[32:47]
	ds_read_b64_tr_b16 v[214:215], v191 offset:0x2600
	ds_read_b64_tr_b16 v[216:217], v191 offset:0x2e00
	ds_read_b64_tr_b16 v[238:239], v191 offset:0x3600
	ds_read_b64_tr_b16 v[240:241], v191 offset:0x3e00
	s_waitcnt lgkmcnt(0)
	v_mfma_f32_32x32x16_bf16 v[32:47], v[92:95], v[234:237], v[32:47]
	v_mfma_f32_32x32x16_bf16 v[48:63], v[80:83], v[206:209], v[48:63]
	v_mfma_f32_32x32x16_bf16 v[48:63], v[84:87], v[210:213], v[48:63]
	v_mfma_f32_32x32x16_bf16 v[48:63], v[88:91], v[214:217], v[48:63]
	v_mfma_f32_32x32x16_bf16 v[48:63], v[92:95], v[238:241], v[48:63]
	v_mov_b64 v[80:81], v[110:111]
	v_mov_b64 v[82:83], v[108:109]
	v_mov_b64 v[84:85], v[106:107]
	v_mov_b64 v[86:87], v[104:105]
	v_mov_b64 v[88:89], v[102:103]
	v_mov_b64 v[90:91], v[100:101]
	v_mov_b64 v[92:93], v[98:99]
	v_mov_b64 v[94:95], v[96:97]
	v_exp_f32_e32 v212, v92
	v_exp_f32_e32 v214, v94
	v_exp_f32_e32 v216, v95
	v_exp_f32_e32 v215, v93
	v_exp_f32_e32 v211, v90
	v_exp_f32_e32 v213, v91
	v_exp_f32_e32 v209, v88
	v_exp_f32_e32 v210, v89
	v_exp_f32_e32 v206, v86
	v_exp_f32_e32 v208, v87
	v_exp_f32_e32 v177, v84
	v_exp_f32_e32 v207, v85
	v_exp_f32_e32 v171, v82
	v_exp_f32_e32 v175, v83
	v_exp_f32_e32 v169, v80
	v_exp_f32_e32 v173, v81
	s_barrier
	s_waitcnt vmcnt(0)
	s_waitcnt vmcnt(3)
	ds_write_b128 v194, v[218:221] offset:16384
	s_waitcnt vmcnt(1)
	ds_write_b128 v195, v[226:229] offset:16384
	ds_write_b128 v196, v[222:225] offset:49152
	s_waitcnt vmcnt(0)
	ds_write_b128 v197, v[230:233] offset:49152
	s_add_i32 s66, s66, 2
	s_mov_b64 s[80:81], 0x60000
	v_add_u32_e32 v148, 0x30000, v148
	s_cmp_ge_u32 s66, s37
	v_lshl_add_u64 v[178:179], v[178:179], 0, s[80:81]
	s_waitcnt lgkmcnt(0)
	s_barrier
	s_cbranch_scc0 .LBB0_286
	ds_read_b128 v[80:83], v198 offset:49152
	ds_read_b128 v[84:87], v198 offset:57344
	s_waitcnt lgkmcnt(1)
	v_mfma_f32_32x32x16_bf16 v[96:111], v[80:83], v[140:143], 0
	s_nop 0
	v_exp_f32_e32 v79, v79
	s_waitcnt lgkmcnt(0)
	v_mfma_f32_32x32x16_bf16 v[80:95], v[84:87], v[140:143], 0
	ds_read_b128 v[140:143], v199 offset:49152
	ds_read_b128 v[218:221], v199 offset:57344
	s_waitcnt lgkmcnt(1)
	v_mfma_f32_32x32x16_bf16 v[96:111], v[140:143], v[136:139], v[96:111]
	s_waitcnt lgkmcnt(0)
	v_mfma_f32_32x32x16_bf16 v[80:95], v[218:221], v[136:139], v[80:95]
	ds_read_b128 v[136:139], v200 offset:49152
	ds_read_b128 v[140:143], v200 offset:57344
	s_waitcnt lgkmcnt(1)
	v_mfma_f32_32x32x16_bf16 v[96:111], v[136:139], v[132:135], v[96:111]
	s_waitcnt lgkmcnt(0)
	v_mfma_f32_32x32x16_bf16 v[80:95], v[140:143], v[132:135], v[80:95]
	ds_read_b128 v[132:135], v201 offset:49152
	ds_read_b128 v[136:139], v201 offset:57344
	s_waitcnt lgkmcnt(1)
	v_mfma_f32_32x32x16_bf16 v[96:111], v[132:135], v[128:131], v[96:111]
	s_waitcnt lgkmcnt(0)
	v_mfma_f32_32x32x16_bf16 v[80:95], v[136:139], v[128:131], v[80:95]
	ds_read_b128 v[128:131], v202 offset:49152
	ds_read_b128 v[132:135], v202 offset:57344
	s_waitcnt lgkmcnt(1)
	v_mfma_f32_32x32x16_bf16 v[96:111], v[128:131], v[124:127], v[96:111]
	s_waitcnt lgkmcnt(0)
	v_mfma_f32_32x32x16_bf16 v[80:95], v[132:135], v[124:127], v[80:95]
	ds_read_b128 v[124:127], v203 offset:49152
	ds_read_b128 v[128:131], v203 offset:57344
	s_waitcnt lgkmcnt(1)
	v_mfma_f32_32x32x16_bf16 v[96:111], v[124:127], v[120:123], v[96:111]
	s_waitcnt lgkmcnt(0)
	v_mfma_f32_32x32x16_bf16 v[80:95], v[128:131], v[120:123], v[80:95]
	ds_read_b128 v[120:123], v204 offset:49152
	ds_read_b128 v[124:127], v204 offset:57344
	s_waitcnt lgkmcnt(1)
	v_mfma_f32_32x32x16_bf16 v[96:111], v[120:123], v[116:119], v[96:111]
	s_waitcnt lgkmcnt(0)
	v_mfma_f32_32x32x16_bf16 v[80:95], v[124:127], v[116:119], v[80:95]
	ds_read_b128 v[116:119], v205 offset:49152
	ds_read_b128 v[120:123], v205 offset:57344
	v_exp_f32_e32 v124, v76
	v_exp_f32_e32 v125, v77
	v_exp_f32_e32 v126, v78
	s_waitcnt lgkmcnt(1)
	v_mfma_f32_32x32x16_bf16 v[96:111], v[116:119], v[112:115], v[96:111]
	v_exp_f32_e32 v116, v68
	v_exp_f32_e32 v117, v69
	v_exp_f32_e32 v118, v70
	v_exp_f32_e32 v119, v71
	s_waitcnt lgkmcnt(0)
; __device__ __forceinline__ void finishSM(f32x16& p0, f32x16& p1, const float negb, float& l_reg, bf16x8& pa0, bf16x8& pa1, bf16x8& pa2, bf16x8& pa3) {
;   p1 = p1 + negb; for (int r = 0; r < 16; ++r) p1[r] = __builtin_amdgcn_exp2f(p1[r]);
;   float ps = 0; for (int r = 0; r < 16; ++r) ps += p0[r]; for (int r = 0; r < 16; ++r) ps += p1[r];
;   l_reg += ps;
;     ...
;   PK4(p0, 0, pa0); PK4(p0, 8, pa1); PK4(p1, 0, pa2); PK4(p1, 8, pa3);
;     ...
; }
; __device__ __forceinline__ void qkt(f32x16& p0, f32x16& p1, const bf16* Ks, const bf16x8* qr, int r32, int hi) {
;   p0 = f32x16{}; p1 = f32x16{};
;   for (int d0 = 0; d0 < 8; ++d0) { int cb = (d0 * 16 + hi * 8) * 2;
;     bf16x8 b0 = *reinterpret_cast<const bf16x8*>((const char*)Ks + KSWZ(r32, cb));
;     bf16x8 b1 = *reinterpret_cast<const bf16x8*>((const char*)Ks + KSWZ(32 + r32, cb));
;     p0 = __builtin_amdgcn_mfma_f32_32x32x16_bf16(b0, qr[d0], p0, 0, 0, 0);
;     p1 = __builtin_amdgcn_mfma_f32_32x32x16_bf16(b1, qr[d0], p1, 0, 0, 0); }
; }
; __device__ __forceinline__ int v_st(int k, int c) { const int kk = (k & ~0xC) | ((k & 4) << 1) | ((k & 8) >> 1); return ((kk >> 3) * 4 + (c >> 5)) * 512 + ((kk & 7) * 32 + (c & 31)) * 2; }
; __device__ __forceinline__ int v_rd_base(int lane) { return ((lane & 3) << 3) | (((lane >> 2) & 3) << 6) | (((lane >> 4) & 1) << 5) | (((lane >> 5) & 1) << 8); }
; template <int OFF> __device__ __forceinline__ s16x4 tr_read(int vb) {
;   s16x4 r; asm volatile("ds_read_b64_tr_b16 %0, %1 offset:%2" : "=&v"(r) : "v"(vb), "i"(OFF) : "memory"); return r;
; }
; template <int D0> __device__ __forceinline__ void pv_one(f32x16& od, int vb, bf16x8 pa0, bf16x8 pa1, bf16x8 pa2, bf16x8 pa3) {
;   const s16x4 l0 = tr_read<v_rd_off(D0, 0, 0)>(vb), h0 = tr_read<v_rd_off(D0, 0, 1)>(vb), l1 = tr_read<v_rd_off(D0, 1, 0)>(vb), h1 = tr_read<v_rd_off(D0, 1, 1)>(vb);
;   const s16x4 l2 = tr_read<v_rd_off(D0, 2, 0)>(vb), h2 = tr_read<v_rd_off(D0, 2, 1)>(vb), l3 = tr_read<v_rd_off(D0, 3, 0)>(vb), h3 = tr_read<v_rd_off(D0, 3, 1)>(vb);
;   asm volatile("s_waitcnt lgkmcnt(0)" ::: "memory"); SBAR();
;     ...
;   od = __builtin_amdgcn_mfma_f32_32x32x16_bf16(pa0, PK(l0, h0), od, 0, 0, 0);
;   od = __builtin_amdgcn_mfma_f32_32x32x16_bf16(pa1, PK(l1, h1), od, 0, 0, 0);
;   od = __builtin_amdgcn_mfma_f32_32x32x16_bf16(pa2, PK(l2, h2), od, 0, 0, 0);
;   od = __builtin_amdgcn_mfma_f32_32x32x16_bf16(pa3, PK(l3, h3), od, 0, 0, 0);
;     ...
; }
	v_mfma_f32_32x32x16_bf16 v[80:95], v[120:123], v[112:115], v[80:95]
	v_exp_f32_e32 v112, v64
	v_add_f32_e32 v64, 0, v214
	v_add_f32_e32 v64, v216, v64
	v_add_f32_e32 v64, v212, v64
	v_add_f32_e32 v64, v215, v64
	v_add_f32_e32 v64, v211, v64
	v_add_f32_e32 v64, v213, v64
	v_add_f32_e32 v64, v209, v64
	v_add_f32_e32 v64, v210, v64
	v_add_f32_e32 v64, v206, v64
	v_add_f32_e32 v64, v208, v64
	v_add_f32_e32 v64, v177, v64
	v_add_f32_e32 v64, v207, v64
	v_add_f32_e32 v64, v171, v64
	v_exp_f32_e32 v113, v65
	v_add_f32_e32 v64, v175, v64
	v_exp_f32_e32 v114, v66
	v_add_f32_e32 v64, v169, v64
	v_exp_f32_e32 v115, v67
	v_add_f32_e32 v64, v173, v64
	v_add_f32_e32 v64, v112, v64
	v_add_f32_e32 v64, v113, v64
	v_add_f32_e32 v64, v114, v64
	v_add_f32_e32 v64, v115, v64
	v_exp_f32_e32 v120, v72
	v_add_f32_e32 v64, v116, v64
	v_exp_f32_e32 v121, v73
	v_add_f32_e32 v64, v117, v64
	v_exp_f32_e32 v122, v74
	v_add_f32_e32 v64, v118, v64
	v_exp_f32_e32 v123, v75
	v_add_f32_e32 v64, v119, v64
	v_add_f32_e32 v64, v120, v64
	v_add_f32_e32 v64, v121, v64
	v_add_f32_e32 v64, v122, v64
	v_add_f32_e32 v64, v123, v64
	v_add_f32_e32 v64, v124, v64
	v_add_f32_e32 v64, v125, v64
	v_add_f32_e32 v64, v126, v64
	v_add_f32_e32 v64, v79, v64
	v_add_f32_e32 v132, v167, v64
	v_cvt_pk_bf16_f32 v64, v214, v216
	v_cvt_pk_bf16_f32 v65, v212, v215
	v_cvt_pk_bf16_f32 v66, v211, v213
	v_cvt_pk_bf16_f32 v67, v209, v210
	v_cvt_pk_bf16_f32 v68, v206, v208
	v_cvt_pk_bf16_f32 v69, v177, v207
	v_cvt_pk_bf16_f32 v70, v171, v175
	v_cvt_pk_bf16_f32 v71, v169, v173
	s_nop 0
	v_permlane32_swap_b32_e32 v64, v66
	v_permlane32_swap_b32_e32 v65, v67
	v_cvt_pk_bf16_f32 v72, v112, v113
	v_cvt_pk_bf16_f32 v73, v114, v115
	v_cvt_pk_bf16_f32 v74, v116, v117
	v_cvt_pk_bf16_f32 v75, v118, v119
	v_cvt_pk_bf16_f32 v76, v120, v121
	v_cvt_pk_bf16_f32 v77, v122, v123
	v_cvt_pk_bf16_f32 v78, v124, v125
	v_cvt_pk_bf16_f32 v79, v126, v79
	v_permlane32_swap_b32_e32 v68, v70
	v_permlane32_swap_b32_e32 v69, v71
	v_permlane32_swap_b32_e32 v72, v74
	v_permlane32_swap_b32_e32 v73, v75
	v_permlane32_swap_b32_e32 v76, v78
	v_permlane32_swap_b32_e32 v77, v79
	ds_read_b64_tr_b16 v[112:113], v181 offset:0
	ds_read_b64_tr_b16 v[114:115], v181 offset:0x800
	ds_read_b64_tr_b16 v[116:117], v181 offset:0x1000
	ds_read_b64_tr_b16 v[118:119], v181 offset:0x1800
	ds_read_b64_tr_b16 v[120:121], v181 offset:0x2000
	ds_read_b64_tr_b16 v[122:123], v181 offset:0x2800
	ds_read_b64_tr_b16 v[124:125], v181 offset:0x3000
	ds_read_b64_tr_b16 v[126:127], v181 offset:0x3800
	s_waitcnt lgkmcnt(0)
	s_nop 0
	v_mfma_f32_32x32x16_bf16 v[0:15], v[64:67], v[112:115], v[0:15]
	ds_read_b64_tr_b16 v[112:113], v181 offset:0x200
	ds_read_b64_tr_b16 v[114:115], v181 offset:0xa00
	v_mfma_f32_32x32x16_bf16 v[0:15], v[68:71], v[116:119], v[0:15]
	ds_read_b64_tr_b16 v[116:117], v181 offset:0x1200
	ds_read_b64_tr_b16 v[118:119], v181 offset:0x1a00
	v_mfma_f32_32x32x16_bf16 v[0:15], v[72:75], v[120:123], v[0:15]
	ds_read_b64_tr_b16 v[120:121], v181 offset:0x2200
	ds_read_b64_tr_b16 v[122:123], v181 offset:0x2a00
	ds_read_b64_tr_b16 v[128:129], v181 offset:0x3200
	ds_read_b64_tr_b16 v[130:131], v181 offset:0x3a00
	s_waitcnt lgkmcnt(0)
	v_mfma_f32_32x32x16_bf16 v[0:15], v[76:79], v[124:127], v[0:15]
	v_mfma_f32_32x32x16_bf16 v[16:31], v[64:67], v[112:115], v[16:31]
	ds_read_b64_tr_b16 v[112:113], v181 offset:0x400
	ds_read_b64_tr_b16 v[114:115], v181 offset:0xc00
	v_mfma_f32_32x32x16_bf16 v[16:31], v[68:71], v[116:119], v[16:31]
	ds_read_b64_tr_b16 v[116:117], v181 offset:0x1400
	ds_read_b64_tr_b16 v[118:119], v181 offset:0x1c00
	v_mfma_f32_32x32x16_bf16 v[16:31], v[72:75], v[120:123], v[16:31]
	ds_read_b64_tr_b16 v[120:121], v181 offset:0x2400
	ds_read_b64_tr_b16 v[122:123], v181 offset:0x2c00
	ds_read_b64_tr_b16 v[124:125], v181 offset:0x3400
	ds_read_b64_tr_b16 v[126:127], v181 offset:0x3c00
	s_waitcnt lgkmcnt(0)
	v_mfma_f32_32x32x16_bf16 v[16:31], v[76:79], v[128:131], v[16:31]
	v_mfma_f32_32x32x16_bf16 v[32:47], v[64:67], v[112:115], v[32:47]
	ds_read_b64_tr_b16 v[112:113], v181 offset:0x600
	ds_read_b64_tr_b16 v[114:115], v181 offset:0xe00
	v_mfma_f32_32x32x16_bf16 v[32:47], v[68:71], v[116:119], v[32:47]
	ds_read_b64_tr_b16 v[116:117], v181 offset:0x1600
	ds_read_b64_tr_b16 v[118:119], v181 offset:0x1e00
	v_mfma_f32_32x32x16_bf16 v[32:47], v[72:75], v[120:123], v[32:47]
	ds_read_b64_tr_b16 v[120:121], v181 offset:0x2600
	ds_read_b64_tr_b16 v[122:123], v181 offset:0x2e00
	ds_read_b64_tr_b16 v[128:129], v181 offset:0x3600
	ds_read_b64_tr_b16 v[130:131], v181 offset:0x3e00
	s_waitcnt lgkmcnt(0)
	v_mfma_f32_32x32x16_bf16 v[32:47], v[76:79], v[124:127], v[32:47]
	v_mfma_f32_32x32x16_bf16 v[48:63], v[64:67], v[112:115], v[48:63]
	v_mov_b64 v[66:67], v[96:97]
	v_mov_b64 v[64:65], v[98:99]
	v_exp_f32_e32 v96, v66
	v_exp_f32_e32 v97, v67
	v_exp_f32_e32 v98, v64
	v_exp_f32_e32 v99, v65
	v_mfma_f32_32x32x16_bf16 v[48:63], v[68:71], v[116:119], v[48:63]
	v_mov_b64 v[64:65], v[94:95]
	v_exp_f32_e32 v100, v100
	v_mov_b64 v[68:69], v[90:91]
	v_exp_f32_e32 v90, v64
	v_add_f32_e32 v64, 0, v96
	v_exp_f32_e32 v101, v101
	v_add_f32_e32 v64, v97, v64
	v_exp_f32_e32 v102, v102
	v_add_f32_e32 v64, v98, v64
	v_exp_f32_e32 v103, v103
	v_mfma_f32_32x32x16_bf16 v[48:63], v[72:75], v[120:123], v[48:63]
	v_add_f32_e32 v64, v99, v64
	v_exp_f32_e32 v104, v104
	v_add_f32_e32 v64, v100, v64
	v_exp_f32_e32 v105, v105
	v_add_f32_e32 v64, v101, v64
	v_exp_f32_e32 v106, v106
	v_add_f32_e32 v64, v102, v64
	v_exp_f32_e32 v107, v107
	v_add_f32_e32 v64, v103, v64
	v_exp_f32_e32 v108, v108
	v_add_f32_e32 v64, v104, v64
	v_exp_f32_e32 v109, v109
	v_add_f32_e32 v64, v105, v64
	v_exp_f32_e32 v110, v110
	v_add_f32_e32 v64, v106, v64
	v_exp_f32_e32 v111, v111
	v_mfma_f32_32x32x16_bf16 v[48:63], v[76:79], v[128:131], v[48:63]
	v_mov_b64 v[78:79], v[80:81]
	v_add_f32_e32 v64, v107, v64
	v_exp_f32_e32 v78, v78
	v_add_f32_e32 v64, v108, v64
	v_mov_b64 v[76:77], v[82:83]
	v_exp_f32_e32 v79, v79
	v_add_f32_e32 v64, v109, v64
	v_exp_f32_e32 v76, v76
	v_add_f32_e32 v64, v110, v64
	v_mov_b64 v[74:75], v[84:85]
	v_exp_f32_e32 v77, v77
	v_add_f32_e32 v64, v111, v64
	v_exp_f32_e32 v80, v74
	v_add_f32_e32 v64, v78, v64
	v_mov_b64 v[72:73], v[86:87]
	v_exp_f32_e32 v81, v75
	v_add_f32_e32 v64, v79, v64
	v_exp_f32_e32 v82, v72
	v_add_f32_e32 v64, v76, v64
	v_mov_b64 v[70:71], v[88:89]
	v_exp_f32_e32 v83, v73
	v_add_f32_e32 v64, v77, v64
	v_exp_f32_e32 v84, v70
	v_add_f32_e32 v64, v80, v64
	v_exp_f32_e32 v85, v71
	v_add_f32_e32 v64, v81, v64
	v_exp_f32_e32 v86, v68
	v_add_f32_e32 v64, v82, v64
	v_mov_b64 v[66:67], v[92:93]
	v_exp_f32_e32 v87, v69
	v_add_f32_e32 v64, v83, v64
	v_exp_f32_e32 v88, v66
	v_add_f32_e32 v64, v84, v64
	v_exp_f32_e32 v89, v67
	v_add_f32_e32 v64, v85, v64
	v_add_f32_e32 v64, v86, v64
	v_exp_f32_e32 v65, v65
	v_add_f32_e32 v64, v87, v64
	v_add_f32_e32 v64, v88, v64
	v_add_f32_e32 v64, v89, v64
	v_add_f32_e32 v64, v90, v64
	v_add_f32_e32 v64, v65, v64
	s_barrier
; #define SBAR() __builtin_amdgcn_sched_barrier(0)
; __device__ __forceinline__ void finishSM(f32x16& p0, f32x16& p1, const float negb, float& l_reg, bf16x8& pa0, bf16x8& pa1, bf16x8& pa2, bf16x8& pa3) {
;   p1 = p1 + negb; for (int r = 0; r < 16; ++r) p1[r] = __builtin_amdgcn_exp2f(p1[r]);
;   float ps = 0; for (int r = 0; r < 16; ++r) ps += p0[r]; for (int r = 0; r < 16; ++r) ps += p1[r];
;   l_reg += ps;
;     ...
;   PK4(p0, 0, pa0); PK4(p0, 8, pa1); PK4(p1, 0, pa2); PK4(p1, 8, pa3);
;     ...
; }
; __device__ __forceinline__ void attn_dense_body(const bf16* __restrict__ Qb, const bf16* __restrict__ Kh, const bf16* __restrict__ Vh,
;                                                 bf16* __restrict__ Ob, int seq, char* lds, const float negb) {
;     ...
;   finishSM(pB0, pB1, negb, l_reg, pa0, pa1, pa2, pa3); SBAR();
;   pv_d0(o, vb0 + (int)SHM_V, pa0, pa1, pa2, pa3);
;   { auto rr = __builtin_amdgcn_permlane32_swap(__float_as_uint(l_reg), __float_as_uint(l_reg), false, false); l_reg = __uint_as_float(rr[0]) + __uint_as_float(rr[1]); }
;   if (hi == 0) li_l[r32] = l_reg; asm volatile("s_waitcnt lgkmcnt(0)" ::: "memory");
	v_add_f32_e32 v64, v132, v64
	v_cvt_pk_bf16_f32 v66, v96, v97
	v_cvt_pk_bf16_f32 v67, v98, v99
	v_cvt_pk_bf16_f32 v68, v100, v101
	v_cvt_pk_bf16_f32 v69, v102, v103
	v_cvt_pk_bf16_f32 v70, v104, v105
	v_cvt_pk_bf16_f32 v71, v106, v107
	v_cvt_pk_bf16_f32 v72, v108, v109
	v_cvt_pk_bf16_f32 v73, v110, v111
	v_cvt_pk_bf16_f32 v74, v78, v79
	v_cvt_pk_bf16_f32 v75, v76, v77
	v_cvt_pk_bf16_f32 v76, v80, v81
	v_cvt_pk_bf16_f32 v77, v82, v83
	v_cvt_pk_bf16_f32 v78, v84, v85
	v_cvt_pk_bf16_f32 v79, v86, v87
	v_cvt_pk_bf16_f32 v80, v88, v89
	v_cvt_pk_bf16_f32 v81, v90, v65
	s_nop 0
	v_permlane32_swap_b32_e32 v66, v68
	v_permlane32_swap_b32_e32 v67, v69
	v_permlane32_swap_b32_e32 v70, v72
	v_permlane32_swap_b32_e32 v71, v73
	v_permlane32_swap_b32_e32 v74, v76
	v_permlane32_swap_b32_e32 v75, v77
	v_permlane32_swap_b32_e32 v78, v80
	v_permlane32_swap_b32_e32 v79, v81
	ds_read_b64_tr_b16 v[82:83], v191 offset:0
	ds_read_b64_tr_b16 v[84:85], v191 offset:0x800
	ds_read_b64_tr_b16 v[86:87], v191 offset:0x1000
	ds_read_b64_tr_b16 v[88:89], v191 offset:0x1800
	ds_read_b64_tr_b16 v[90:91], v191 offset:0x2000
	ds_read_b64_tr_b16 v[92:93], v191 offset:0x2800
	ds_read_b64_tr_b16 v[94:95], v191 offset:0x3000
	ds_read_b64_tr_b16 v[96:97], v191 offset:0x3800
	s_waitcnt lgkmcnt(0)
	s_nop 0
	v_mfma_f32_32x32x16_bf16 v[0:15], v[66:69], v[82:85], v[0:15]
	ds_read_b64_tr_b16 v[82:83], v191 offset:0x200
	ds_read_b64_tr_b16 v[84:85], v191 offset:0xa00
	v_mfma_f32_32x32x16_bf16 v[0:15], v[70:73], v[86:89], v[0:15]
	ds_read_b64_tr_b16 v[86:87], v191 offset:0x1200
	ds_read_b64_tr_b16 v[88:89], v191 offset:0x1a00
	v_mfma_f32_32x32x16_bf16 v[0:15], v[74:77], v[90:93], v[0:15]
	ds_read_b64_tr_b16 v[90:91], v191 offset:0x2200
	ds_read_b64_tr_b16 v[92:93], v191 offset:0x2a00
	ds_read_b64_tr_b16 v[98:99], v191 offset:0x3200
	ds_read_b64_tr_b16 v[100:101], v191 offset:0x3a00
	s_waitcnt lgkmcnt(0)
	v_mfma_f32_32x32x16_bf16 v[0:15], v[78:81], v[94:97], v[0:15]
	v_mfma_f32_32x32x16_bf16 v[16:31], v[66:69], v[82:85], v[16:31]
	ds_read_b64_tr_b16 v[82:83], v191 offset:0x400
	ds_read_b64_tr_b16 v[84:85], v191 offset:0xc00
	v_mfma_f32_32x32x16_bf16 v[16:31], v[70:73], v[86:89], v[16:31]
	ds_read_b64_tr_b16 v[86:87], v191 offset:0x1400
	ds_read_b64_tr_b16 v[88:89], v191 offset:0x1c00
	v_mfma_f32_32x32x16_bf16 v[16:31], v[74:77], v[90:93], v[16:31]
	ds_read_b64_tr_b16 v[90:91], v191 offset:0x2400
	ds_read_b64_tr_b16 v[92:93], v191 offset:0x2c00
	ds_read_b64_tr_b16 v[94:95], v191 offset:0x3400
	ds_read_b64_tr_b16 v[96:97], v191 offset:0x3c00
	s_waitcnt lgkmcnt(0)
	v_mfma_f32_32x32x16_bf16 v[16:31], v[78:81], v[98:101], v[16:31]
	v_mfma_f32_32x32x16_bf16 v[32:47], v[66:69], v[82:85], v[32:47]
	ds_read_b64_tr_b16 v[82:83], v191 offset:0x600
	ds_read_b64_tr_b16 v[84:85], v191 offset:0xe00
	v_mfma_f32_32x32x16_bf16 v[32:47], v[70:73], v[86:89], v[32:47]
	ds_read_b64_tr_b16 v[86:87], v191 offset:0x1600
	ds_read_b64_tr_b16 v[88:89], v191 offset:0x1e00
	v_mfma_f32_32x32x16_bf16 v[32:47], v[74:77], v[90:93], v[32:47]
	ds_read_b64_tr_b16 v[90:91], v191 offset:0x2600
	ds_read_b64_tr_b16 v[92:93], v191 offset:0x2e00
	ds_read_b64_tr_b16 v[98:99], v191 offset:0x3600
	ds_read_b64_tr_b16 v[100:101], v191 offset:0x3e00
	s_waitcnt lgkmcnt(0)
	v_mfma_f32_32x32x16_bf16 v[32:47], v[78:81], v[94:97], v[32:47]
	v_mfma_f32_32x32x16_bf16 v[48:63], v[66:69], v[82:85], v[48:63]
	v_mov_b32_e32 v65, v64
	s_nop 1
	v_permlane32_swap_b32_e32 v64, v65
	v_mfma_f32_32x32x16_bf16 v[48:63], v[70:73], v[86:89], v[48:63]
	v_mfma_f32_32x32x16_bf16 v[48:63], v[74:77], v[90:93], v[48:63]
	v_mfma_f32_32x32x16_bf16 v[48:63], v[78:81], v[98:101], v[48:63]
	s_and_saveexec_b64 s[62:63], s[4:5]
	s_cbranch_execz .LBB0_282
	v_add_f32_e32 v64, v64, v65
	ds_write_b32 v192, v64
	s_branch .LBB0_282

; __device__ __forceinline__ void expA(f32x16& p0, const float negb) { p0 = p0 + negb; for (int r = 0; r < 16; ++r) p0[r] = __builtin_amdgcn_exp2f(p0[r]); }
; __device__ __forceinline__ int v_st(int k, int c) { const int kk = (k & ~0xC) | ((k & 4) << 1) | ((k & 8) >> 1); return ((kk >> 3) * 4 + (c >> 5)) * 512 + ((kk & 7) * 32 + (c & 31)) * 2; }
; __device__ __forceinline__ int v_rd_base(int lane) { return ((lane & 3) << 3) | (((lane >> 2) & 3) << 6) | (((lane >> 4) & 1) << 5) | (((lane >> 5) & 1) << 8); }
; #define SLOAD(i, k0) do { const unsigned a_ = (unsigned)(k0) * (unsigned)LDK + so0; sr_[i].vs0 = ld8(Kh + (a_ + 256u)); sr_[i].vs1 = ld8(Kh + (a_ + 32u * LDK + 256u)); \
;     sr_[i].ks0 = ld8(Kh + a_); sr_[i].ks1 = ld8(Kh + (a_ + 32u * LDK)); } while (0)
; #define SWRITE(b, i) do { *(bf16x8*)((char*)V_lds + (b) * SHM_V + vst0) = sr_[i].vs0;          \
;     *(bf16x8*)((char*)V_lds + (b) * SHM_V + vst1) = sr_[i].vs1; int kc = sc * 2;               \
;     *(bf16x8*)((char*)K_lds + (b) * SHM_K + KSWZ(sr, kc)) = sr_[i].ks0;                       \
;     *(bf16x8*)((char*)K_lds + (b) * SHM_K + KSWZ(32 + sr, kc)) = sr_[i].ks1; } while (0)
; __device__ __forceinline__ void attn_dense_body(const bf16* __restrict__ Qb, const bf16* __restrict__ Kh, const bf16* __restrict__ Vh,
;                                                 bf16* __restrict__ Ob, int seq, char* lds, const float negb) {
;     ...
;   const bf16* Qw = Qb + (long)(wid * QBLK + r32) * LDQ + hi * 8;
; #pragma unroll
;   for (int d0 = 0; d0 < 8; ++d0) qr[d0] = ld8(Qw + d0 * 16);
;   const int sr = tid >> 4, sc = (tid & 15) * 8, vst0 = v_st(sr, sc), vst1 = v_st(32 + sr, sc);
;   const int vb0 = (int)(uintptr_t)V_lds + v_rd_base(lane);
;   struct { bf16x8 vs0, vs1, ks0, ks1; } sr_[1];
;   const unsigned so0 = (unsigned)(sr * LDK + sc);
;     ...
;   f32x16 pA0, pA1, pB0, pB1; bf16x8 pa0, pa1, pa2, pa3; const int NT = seq / KVBLK;
;   constexpr int SE = 0, SO = 0;
;   SLOAD(SE, 0); asm volatile("s_waitcnt vmcnt(0)" ::: "memory"); SWRITE(0, SE); __syncthreads();
;   qkt(pA0, pA1, K_lds, qr, r32, hi); expA(pA0, negb);
.LBB0_514:
	s_mul_i32 s4, s79, s88
	s_add_i32 s4, s4, s2
	s_cmpk_gt_i32 s4, 0x4ff
	s_mov_b64 s[60:61], -1
	s_cbranch_scc1 .LBB0_513
	s_add_i32 s60, s4, 0xfffffc00
	s_cmpk_lt_i32 s4, 0x400
	s_cselect_b32 s60, s4, s60
	s_cselect_b32 s61, 8, 7
	s_ashr_i32 s61, s60, s61
	s_lshl_b32 s62, s61, 13
	s_addk_i32 s62, 0x2000
	s_lshl_b32 s61, s61, 12
	s_cmpk_lt_i32 s4, 0x400
	s_cselect_b32 s4, 31, 15
	s_cselect_b32 s63, 5, 4
	s_cselect_b32 s82, 0x80, 64
	s_cselect_b32 s81, s62, s61
	s_and_b32 s4, s60, s4
	s_lshr_b32 s60, s60, s63
	s_and_b32 s84, s60, 7
	s_mul_i32 s64, s81, 0xc00
	s_mul_hi_u32 s65, s81, 0xc00
	s_add_u32 s61, s20, s64
	s_addc_u32 s62, s21, s65
	s_lshl_b32 s60, s60, 6
	s_and_b32 s83, s60, 0x100
	s_add_u32 s60, s61, s83
	s_addc_u32 s61, s62, 0
	s_add_u32 s62, s60, 0x800
	s_addc_u32 s63, s61, 0
	s_lshl_b32 s4, s4, 8
	s_add_i32 s4, s81, s4
	s_mul_i32 s85, s4, 0xc00
	s_mul_hi_u32 s81, s4, 0xc00
	s_add_u32 s85, s20, s85
	s_addc_u32 s86, s21, s81
	s_lshl_b32 s81, s84, 7
	s_lshl_b32 s84, s84, 8
	s_add_u32 s84, s85, s84
	v_mov_b32_e32 v171, v149
	s_addc_u32 s85, s86, 0
	v_mov_b32_e32 v167, v149
	v_lshl_add_u64 v[24:25], s[60:61], 0, v[170:171]
	v_lshl_add_u64 v[0:1], s[84:85], 0, v[166:167]
	v_mov_b32_e32 v169, v149
	v_add_co_u32_e32 v12, vcc, s28, v24
	v_lshl_add_u64 v[0:1], v[0:1], 0, v[168:169]
	s_nop 0
	v_addc_co_u32_e32 v13, vcc, 0, v25, vcc
	global_load_dwordx4 v[140:143], v[0:1], off
	global_load_dwordx4 v[136:139], v[0:1], off offset:32
	global_load_dwordx4 v[132:135], v[0:1], off offset:64
	global_load_dwordx4 v[128:131], v[0:1], off offset:96
	global_load_dwordx4 v[124:127], v[0:1], off offset:128
	global_load_dwordx4 v[120:123], v[0:1], off offset:160
	global_load_dwordx4 v[116:119], v[0:1], off offset:192
	global_load_dwordx4 v[112:115], v[0:1], off offset:224
	v_add_co_u32_e32 v26, vcc, s29, v24
	global_load_dwordx4 v[0:3], v170, s[60:61] offset:2560
	global_load_dwordx4 v[4:7], v[12:13], off offset:2560
	global_load_dwordx4 v[8:11], v170, s[60:61] offset:2048
	s_nop 0
	global_load_dwordx4 v[12:15], v[12:13], off offset:2048
	s_waitcnt vmcnt(0)
	v_addc_co_u32_e32 v27, vcc, 0, v25, vcc
	s_mov_b32 s84, 0x48000
	v_add_co_u32_e32 v28, vcc, s84, v24
	s_or_b32 s64, s64, s83
	s_nop 0
	v_addc_co_u32_e32 v29, vcc, 0, v25, vcc
	v_mov_b32_e32 v167, 0
	v_lshl_add_u64 v[178:179], v[164:165], 0, s[64:65]
	s_mov_b32 s64, 2
	v_mov_b32_e32 v148, v193
	v_mov_b32_e32 v32, 0
	v_mov_b32_e32 v33, v167
	v_mov_b32_e32 v34, v167
	v_mov_b32_e32 v35, v167
	v_mov_b32_e32 v36, v167
	v_mov_b32_e32 v37, v167
	v_mov_b32_e32 v38, v167
	v_mov_b32_e32 v39, v167
	v_mov_b32_e32 v40, v167
	v_mov_b32_e32 v41, v167
	v_mov_b32_e32 v42, v167
	v_mov_b32_e32 v43, v167
	v_mov_b32_e32 v44, v167
	v_mov_b32_e32 v45, v167
	v_mov_b32_e32 v46, v167
	v_mov_b32_e32 v47, v167
	v_mov_b32_e32 v48, 0
	v_mov_b32_e32 v49, v167
	v_mov_b32_e32 v50, v167
	v_mov_b32_e32 v51, v167
	v_mov_b32_e32 v52, v167
	v_mov_b32_e32 v53, v167
	v_mov_b32_e32 v54, v167
	v_mov_b32_e32 v55, v167
	v_mov_b32_e32 v56, v167
	v_mov_b32_e32 v57, v167
	v_mov_b32_e32 v58, v167
	v_mov_b32_e32 v59, v167
	v_mov_b32_e32 v60, v167
	v_mov_b32_e32 v61, v167
	v_mov_b32_e32 v62, v167
	v_mov_b32_e32 v63, v167
	s_waitcnt vmcnt(3)
	ds_write_b128 v194, v[0:3]
	s_waitcnt vmcnt(2)
	ds_write_b128 v195, v[4:7]
	s_waitcnt vmcnt(1)
	ds_write_b128 v196, v[8:11] offset:32768
	s_waitcnt vmcnt(0)
	ds_write_b128 v197, v[12:15] offset:32768
	s_waitcnt lgkmcnt(0)
	s_barrier
	ds_read_b128 v[0:3], v198 offset:32768
	ds_read_b128 v[16:19], v198 offset:40960
	s_waitcnt lgkmcnt(1)
	v_mfma_f32_32x32x16_bf16 v[0:15], v[0:3], v[140:143], 0
	s_waitcnt lgkmcnt(0)
	v_mfma_f32_32x32x16_bf16 v[64:79], v[16:19], v[140:143], 0
	ds_read_b128 v[16:19], v199 offset:32768
	ds_read_b128 v[20:23], v199 offset:40960
	s_waitcnt lgkmcnt(1)
	v_mfma_f32_32x32x16_bf16 v[0:15], v[16:19], v[136:139], v[0:15]
	s_waitcnt lgkmcnt(0)
	v_mfma_f32_32x32x16_bf16 v[64:79], v[20:23], v[136:139], v[64:79]
	ds_read_b128 v[16:19], v200 offset:32768
	ds_read_b128 v[20:23], v200 offset:40960
	s_waitcnt lgkmcnt(1)
	v_mfma_f32_32x32x16_bf16 v[0:15], v[16:19], v[132:135], v[0:15]
	s_waitcnt lgkmcnt(0)
	v_mfma_f32_32x32x16_bf16 v[64:79], v[20:23], v[132:135], v[64:79]
	ds_read_b128 v[16:19], v201 offset:32768
	ds_read_b128 v[20:23], v201 offset:40960
	s_waitcnt lgkmcnt(1)
	v_mfma_f32_32x32x16_bf16 v[0:15], v[16:19], v[128:131], v[0:15]
	s_waitcnt lgkmcnt(0)
	v_mfma_f32_32x32x16_bf16 v[64:79], v[20:23], v[128:131], v[64:79]
	ds_read_b128 v[16:19], v202 offset:32768
	ds_read_b128 v[20:23], v202 offset:40960
	s_waitcnt lgkmcnt(1)
	v_mfma_f32_32x32x16_bf16 v[0:15], v[16:19], v[124:127], v[0:15]
	s_waitcnt lgkmcnt(0)
	v_mfma_f32_32x32x16_bf16 v[64:79], v[20:23], v[124:127], v[64:79]
	ds_read_b128 v[16:19], v203 offset:32768
	ds_read_b128 v[20:23], v203 offset:40960
	s_waitcnt lgkmcnt(1)
	v_mfma_f32_32x32x16_bf16 v[0:15], v[16:19], v[120:123], v[0:15]
	s_waitcnt lgkmcnt(0)
	v_mfma_f32_32x32x16_bf16 v[64:79], v[20:23], v[120:123], v[64:79]
	ds_read_b128 v[16:19], v204 offset:32768
	ds_read_b128 v[20:23], v204 offset:40960
	s_waitcnt lgkmcnt(1)
	v_mfma_f32_32x32x16_bf16 v[0:15], v[16:19], v[116:119], v[0:15]
	s_waitcnt lgkmcnt(0)
	v_mfma_f32_32x32x16_bf16 v[64:79], v[20:23], v[116:119], v[64:79]
	ds_read_b128 v[16:19], v205 offset:32768
	ds_read_b128 v[20:23], v205 offset:40960
	s_waitcnt lgkmcnt(1)
	v_mfma_f32_32x32x16_bf16 v[0:15], v[16:19], v[112:115], v[0:15]
	global_load_dwordx4 v[16:19], v[26:27], off offset:2560
	s_waitcnt lgkmcnt(0)
; #define SBAR() __builtin_amdgcn_sched_barrier(0)
; __device__ __forceinline__ void expA(f32x16& p0, const float negb) { p0 = p0 + negb; for (int r = 0; r < 16; ++r) p0[r] = __builtin_amdgcn_exp2f(p0[r]); }
; #define SLOAD(i, k0) do { const unsigned a_ = (unsigned)(k0) * (unsigned)LDK + so0; sr_[i].vs0 = ld8(Kh + (a_ + 256u)); sr_[i].vs1 = ld8(Kh + (a_ + 32u * LDK + 256u)); \
;     sr_[i].ks0 = ld8(Kh + a_); sr_[i].ks1 = ld8(Kh + (a_ + 32u * LDK)); } while (0)
; #define SWRITE(b, i) do { *(bf16x8*)((char*)V_lds + (b) * SHM_V + vst0) = sr_[i].vs0;          \
;     *(bf16x8*)((char*)V_lds + (b) * SHM_V + vst1) = sr_[i].vs1; int kc = sc * 2;               \
;     *(bf16x8*)((char*)K_lds + (b) * SHM_K + KSWZ(sr, kc)) = sr_[i].ks0;                       \
;     *(bf16x8*)((char*)K_lds + (b) * SHM_K + KSWZ(32 + sr, kc)) = sr_[i].ks1; } while (0)
; #define SWAIT() asm volatile("s_waitcnt vmcnt(0)" ::: "memory")
; __device__ __forceinline__ void finishSM(f32x16& p0, f32x16& p1, const float negb, float& l_reg, bf16x8& pa0, bf16x8& pa1, bf16x8& pa2, bf16x8& pa3) {
;   p1 = p1 + negb; for (int r = 0; r < 16; ++r) p1[r] = __builtin_amdgcn_exp2f(p1[r]);
;   float ps = 0; for (int r = 0; r < 16; ++r) ps += p0[r]; for (int r = 0; r < 16; ++r) ps += p1[r];
; __device__ __forceinline__ void attn_dense_body(const bf16* __restrict__ Qb, const bf16* __restrict__ Kh, const bf16* __restrict__ Vh,
;                                                 bf16* __restrict__ Ob, int seq, char* lds, const float negb) {
;     ...
;   SLOAD(SE, 0); asm volatile("s_waitcnt vmcnt(0)" ::: "memory"); SWRITE(0, SE); __syncthreads();
;   qkt(pA0, pA1, K_lds, qr, r32, hi); expA(pA0, negb);
;   SLOAD(SO, KVBLK);
;   SWAIT(); SWRITE(1, SO); __syncthreads();
;   for (int j = 1; j + 1 < NT; j += 2) {
;     SBAR(); qkt(pB0, pB1, (bf16*)((char*)K_lds + SHM_K), qr, r32, hi);
;     finishSM(pA0, pA1, negb, l_reg, pa0, pa1, pa2, pa3); SBAR();
	v_mfma_f32_32x32x16_bf16 v[64:79], v[20:23], v[112:115], v[64:79]
	global_load_dwordx4 v[20:23], v[28:29], off offset:2560
	s_nop 0
	global_load_dwordx4 v[24:27], v[26:27], off offset:2048
	s_nop 0
	global_load_dwordx4 v[28:31], v[28:29], off offset:2048
	s_nop 3
	v_exp_f32_e32 v212, v2
	v_exp_f32_e32 v214, v0
	v_exp_f32_e32 v216, v1
	v_exp_f32_e32 v215, v3
	v_exp_f32_e32 v211, v4
	v_exp_f32_e32 v213, v5
	v_exp_f32_e32 v209, v6
	v_exp_f32_e32 v210, v7
	v_exp_f32_e32 v206, v8
	v_exp_f32_e32 v208, v9
	v_exp_f32_e32 v177, v10
	v_exp_f32_e32 v207, v11
	v_exp_f32_e32 v171, v12
	v_exp_f32_e32 v175, v13
	v_exp_f32_e32 v169, v14
	v_exp_f32_e32 v173, v15
	s_waitcnt vmcnt(0)
	s_waitcnt vmcnt(3)
	ds_write_b128 v194, v[16:19] offset:16384
	s_waitcnt vmcnt(2)
	ds_write_b128 v195, v[20:23] offset:16384
	s_waitcnt vmcnt(1)
	ds_write_b128 v196, v[24:27] offset:49152
	s_waitcnt vmcnt(0)
	ds_write_b128 v197, v[28:31] offset:49152
	v_mov_b32_e32 v0, 0
	v_mov_b32_e32 v1, v167
	v_mov_b32_e32 v2, v167
	v_mov_b32_e32 v3, v167
	v_mov_b32_e32 v4, v167
	v_mov_b32_e32 v5, v167
	v_mov_b32_e32 v6, v167
	v_mov_b32_e32 v7, v167
	v_mov_b32_e32 v8, v167
	v_mov_b32_e32 v9, v167
	v_mov_b32_e32 v10, v167
	v_mov_b32_e32 v11, v167
	v_mov_b32_e32 v12, v167
	v_mov_b32_e32 v13, v167
	v_mov_b32_e32 v14, v167
	v_mov_b32_e32 v15, v167
	v_mov_b32_e32 v16, 0
	v_mov_b32_e32 v17, v167
	v_mov_b32_e32 v18, v167
	v_mov_b32_e32 v19, v167
	v_mov_b32_e32 v20, v167
	v_mov_b32_e32 v21, v167
	v_mov_b32_e32 v22, v167
	v_mov_b32_e32 v23, v167
	v_mov_b32_e32 v24, v167
	v_mov_b32_e32 v25, v167
	v_mov_b32_e32 v26, v167
	v_mov_b32_e32 v27, v167
	v_mov_b32_e32 v28, v167
	v_mov_b32_e32 v29, v167
	v_mov_b32_e32 v30, v167
	v_mov_b32_e32 v31, v167
	s_waitcnt lgkmcnt(0)
	s_barrier
.LBB0_516:
	ds_read_b128 v[80:83], v198 offset:49152
	ds_read_b128 v[84:87], v198 offset:57344
	ds_read_b128 v[218:221], v199 offset:49152
	ds_read_b128 v[222:225], v199 offset:57344
	s_waitcnt lgkmcnt(3)
	v_mfma_f32_32x32x16_bf16 v[96:111], v[80:83], v[140:143], 0
	v_exp_f32_e32 v188, v64
	v_add_f32_e32 v64, 0, v214
	v_add_f32_e32 v64, v216, v64
	v_add_f32_e32 v64, v212, v64
	v_add_f32_e32 v64, v215, v64
	v_add_f32_e32 v64, v211, v64
	v_add_f32_e32 v64, v213, v64
	s_waitcnt lgkmcnt(2)
	v_mfma_f32_32x32x16_bf16 v[80:95], v[84:87], v[140:143], 0
	v_add_f32_e32 v64, v209, v64
	v_add_f32_e32 v64, v210, v64
	v_add_f32_e32 v64, v206, v64
	v_add_f32_e32 v64, v208, v64
	v_add_f32_e32 v64, v177, v64
	v_add_f32_e32 v64, v207, v64
	v_add_f32_e32 v64, v171, v64
	s_waitcnt lgkmcnt(1)
	v_mfma_f32_32x32x16_bf16 v[96:111], v[218:221], v[136:139], v[96:111]
	v_exp_f32_e32 v189, v65
	v_add_f32_e32 v64, v175, v64
	v_exp_f32_e32 v217, v66
	v_add_f32_e32 v64, v169, v64
	v_add_f32_e32 v64, v173, v64
	v_add_f32_e32 v64, v188, v64
	s_waitcnt lgkmcnt(0)
	v_mfma_f32_32x32x16_bf16 v[80:95], v[222:225], v[136:139], v[80:95]
	ds_read_b128 v[218:221], v200 offset:49152
	ds_read_b128 v[222:225], v200 offset:57344
	v_add_f32_e32 v64, v189, v64
	v_add_f32_e32 v64, v217, v64
	s_waitcnt lgkmcnt(1)
	v_mfma_f32_32x32x16_bf16 v[96:111], v[218:221], v[132:135], v[96:111]
	v_exp_f32_e32 v226, v75
	v_exp_f32_e32 v227, v76
	v_exp_f32_e32 v228, v77
	v_exp_f32_e32 v229, v78
	v_exp_f32_e32 v79, v79
	s_waitcnt lgkmcnt(0)
	v_mfma_f32_32x32x16_bf16 v[80:95], v[222:225], v[132:135], v[80:95]
	ds_read_b128 v[218:221], v201 offset:49152
	ds_read_b128 v[222:225], v201 offset:57344
	s_waitcnt lgkmcnt(1)
	v_mfma_f32_32x32x16_bf16 v[96:111], v[218:221], v[128:131], v[96:111]
	s_waitcnt lgkmcnt(0)
	v_mfma_f32_32x32x16_bf16 v[80:95], v[222:225], v[128:131], v[80:95]
	ds_read_b128 v[218:221], v202 offset:49152
	ds_read_b128 v[222:225], v202 offset:57344
	s_waitcnt lgkmcnt(1)
	v_mfma_f32_32x32x16_bf16 v[96:111], v[218:221], v[124:127], v[96:111]
	s_waitcnt lgkmcnt(0)
	v_mfma_f32_32x32x16_bf16 v[80:95], v[222:225], v[124:127], v[80:95]
	ds_read_b128 v[218:221], v203 offset:49152
	ds_read_b128 v[222:225], v203 offset:57344
	s_waitcnt lgkmcnt(1)
	v_mfma_f32_32x32x16_bf16 v[96:111], v[218:221], v[120:123], v[96:111]
	s_waitcnt lgkmcnt(0)
	v_mfma_f32_32x32x16_bf16 v[80:95], v[222:225], v[120:123], v[80:95]
	ds_read_b128 v[218:221], v204 offset:49152
	ds_read_b128 v[222:225], v204 offset:57344
	s_waitcnt lgkmcnt(1)
	v_mfma_f32_32x32x16_bf16 v[96:111], v[218:221], v[116:119], v[96:111]
	s_waitcnt lgkmcnt(0)
	v_mfma_f32_32x32x16_bf16 v[80:95], v[222:225], v[116:119], v[80:95]
	ds_read_b128 v[218:221], v205 offset:49152
	ds_read_b128 v[222:225], v205 offset:57344
	s_waitcnt lgkmcnt(1)
	v_mfma_f32_32x32x16_bf16 v[96:111], v[218:221], v[112:115], v[96:111]
	v_exp_f32_e32 v218, v67
	v_exp_f32_e32 v219, v68
	v_exp_f32_e32 v220, v69
	v_exp_f32_e32 v221, v70
	v_add_f32_e32 v64, v218, v64
	v_add_f32_e32 v64, v219, v64
	v_add_f32_e32 v64, v220, v64
	s_waitcnt lgkmcnt(0)
; __device__ __forceinline__ void finishSM(f32x16& p0, f32x16& p1, const float negb, float& l_reg, bf16x8& pa0, bf16x8& pa1, bf16x8& pa2, bf16x8& pa3) {
;   p1 = p1 + negb; for (int r = 0; r < 16; ++r) p1[r] = __builtin_amdgcn_exp2f(p1[r]);
;   float ps = 0; for (int r = 0; r < 16; ++r) ps += p0[r]; for (int r = 0; r < 16; ++r) ps += p1[r];
;   l_reg += ps;
;     ...
;   PK4(p0, 0, pa0); PK4(p0, 8, pa1); PK4(p1, 0, pa2); PK4(p1, 8, pa3);
;     ...
; }
; __device__ __forceinline__ void qkt(f32x16& p0, f32x16& p1, const bf16* Ks, const bf16x8* qr, int r32, int hi) {
;   p0 = f32x16{}; p1 = f32x16{};
;   for (int d0 = 0; d0 < 8; ++d0) { int cb = (d0 * 16 + hi * 8) * 2;
;     bf16x8 b0 = *reinterpret_cast<const bf16x8*>((const char*)Ks + KSWZ(r32, cb));
;     bf16x8 b1 = *reinterpret_cast<const bf16x8*>((const char*)Ks + KSWZ(32 + r32, cb));
;     p0 = __builtin_amdgcn_mfma_f32_32x32x16_bf16(b0, qr[d0], p0, 0, 0, 0);
;     p1 = __builtin_amdgcn_mfma_f32_32x32x16_bf16(b1, qr[d0], p1, 0, 0, 0); }
; }
; __device__ __forceinline__ int v_st(int k, int c) { const int kk = (k & ~0xC) | ((k & 4) << 1) | ((k & 8) >> 1); return ((kk >> 3) * 4 + (c >> 5)) * 512 + ((kk & 7) * 32 + (c & 31)) * 2; }
; __device__ __forceinline__ int v_rd_base(int lane) { return ((lane & 3) << 3) | (((lane >> 2) & 3) << 6) | (((lane >> 4) & 1) << 5) | (((lane >> 5) & 1) << 8); }
; template <int OFF> __device__ __forceinline__ s16x4 tr_read(int vb) {
;   s16x4 r; asm volatile("ds_read_b64_tr_b16 %0, %1 offset:%2" : "=&v"(r) : "v"(vb), "i"(OFF) : "memory"); return r;
; }
; template <int D0> __device__ __forceinline__ void pv_one(f32x16& od, int vb, bf16x8 pa0, bf16x8 pa1, bf16x8 pa2, bf16x8 pa3) {
;   const s16x4 l0 = tr_read<v_rd_off(D0, 0, 0)>(vb), h0 = tr_read<v_rd_off(D0, 0, 1)>(vb), l1 = tr_read<v_rd_off(D0, 1, 0)>(vb), h1 = tr_read<v_rd_off(D0, 1, 1)>(vb);
;   const s16x4 l2 = tr_read<v_rd_off(D0, 2, 0)>(vb), h2 = tr_read<v_rd_off(D0, 2, 1)>(vb), l3 = tr_read<v_rd_off(D0, 3, 0)>(vb), h3 = tr_read<v_rd_off(D0, 3, 1)>(vb);
;   asm volatile("s_waitcnt lgkmcnt(0)" ::: "memory"); SBAR();
;     ...
;   od = __builtin_amdgcn_mfma_f32_32x32x16_bf16(pa0, PK(l0, h0), od, 0, 0, 0);
;   od = __builtin_amdgcn_mfma_f32_32x32x16_bf16(pa1, PK(l1, h1), od, 0, 0, 0);
;   od = __builtin_amdgcn_mfma_f32_32x32x16_bf16(pa2, PK(l2, h2), od, 0, 0, 0);
;   od = __builtin_amdgcn_mfma_f32_32x32x16_bf16(pa3, PK(l3, h3), od, 0, 0, 0);
;     ...
; }
	v_mfma_f32_32x32x16_bf16 v[80:95], v[222:225], v[112:115], v[80:95]
	v_exp_f32_e32 v222, v71
	v_exp_f32_e32 v223, v72
	v_exp_f32_e32 v224, v73
	v_exp_f32_e32 v225, v74
	v_add_f32_e32 v64, v221, v64
	v_add_f32_e32 v64, v222, v64
	v_add_f32_e32 v64, v223, v64
	v_add_f32_e32 v64, v224, v64
	v_add_f32_e32 v64, v225, v64
	v_add_f32_e32 v64, v226, v64
	v_add_f32_e32 v64, v227, v64
	v_add_f32_e32 v64, v228, v64
	v_add_f32_e32 v64, v229, v64
	v_add_f32_e32 v64, v79, v64
	v_add_f32_e32 v167, v167, v64
	v_cvt_pk_bf16_f32 v64, v214, v216
	v_cvt_pk_bf16_f32 v65, v212, v215
	v_cvt_pk_bf16_f32 v66, v211, v213
	v_cvt_pk_bf16_f32 v67, v209, v210
	v_cvt_pk_bf16_f32 v68, v206, v208
	v_cvt_pk_bf16_f32 v69, v177, v207
	v_cvt_pk_bf16_f32 v70, v171, v175
	v_cvt_pk_bf16_f32 v71, v169, v173
	v_cvt_pk_bf16_f32 v72, v188, v189
	v_cvt_pk_bf16_f32 v73, v217, v218
	v_cvt_pk_bf16_f32 v74, v219, v220
	v_cvt_pk_bf16_f32 v75, v221, v222
	v_cvt_pk_bf16_f32 v76, v223, v224
	v_cvt_pk_bf16_f32 v77, v225, v226
	v_cvt_pk_bf16_f32 v78, v227, v228
	v_cvt_pk_bf16_f32 v79, v229, v79
	s_nop 0
	v_permlane32_swap_b32_e32 v64, v66
	v_permlane32_swap_b32_e32 v65, v67
	v_permlane32_swap_b32_e32 v68, v70
	v_permlane32_swap_b32_e32 v69, v71
	v_permlane32_swap_b32_e32 v72, v74
	v_permlane32_swap_b32_e32 v73, v75
	v_permlane32_swap_b32_e32 v76, v78
	v_permlane32_swap_b32_e32 v77, v79
	v_add_co_u32_e32 v210, vcc, s34, v178
	s_nop 1
	v_addc_co_u32_e32 v211, vcc, -1, v179, vcc
	global_load_dwordx4 v[206:209], v[210:211], off
	s_nop 0
	global_load_dwordx4 v[210:213], v[210:211], off offset:-512
	s_nop 0
	global_load_dwordx4 v[214:217], v[178:179], off
	global_load_dwordx4 v[218:221], v[178:179], off offset:-512
	ds_read_b64_tr_b16 v[222:223], v181 offset:0
	ds_read_b64_tr_b16 v[224:225], v181 offset:0x800
	ds_read_b64_tr_b16 v[226:227], v181 offset:0x1000
	ds_read_b64_tr_b16 v[228:229], v181 offset:0x1800
	ds_read_b64_tr_b16 v[230:231], v181 offset:0x2000
	ds_read_b64_tr_b16 v[232:233], v181 offset:0x2800
	ds_read_b64_tr_b16 v[234:235], v181 offset:0x3000
	ds_read_b64_tr_b16 v[236:237], v181 offset:0x3800
	s_waitcnt lgkmcnt(0)
	s_nop 0
	v_mfma_f32_32x32x16_bf16 v[0:15], v[64:67], v[222:225], v[0:15]
	ds_read_b64_tr_b16 v[222:223], v181 offset:0x200
	ds_read_b64_tr_b16 v[224:225], v181 offset:0xa00
	v_mfma_f32_32x32x16_bf16 v[0:15], v[68:71], v[226:229], v[0:15]
	ds_read_b64_tr_b16 v[226:227], v181 offset:0x1200
	ds_read_b64_tr_b16 v[228:229], v181 offset:0x1a00
	v_mfma_f32_32x32x16_bf16 v[0:15], v[72:75], v[230:233], v[0:15]
	ds_read_b64_tr_b16 v[230:231], v181 offset:0x2200
	ds_read_b64_tr_b16 v[232:233], v181 offset:0x2a00
	ds_read_b64_tr_b16 v[238:239], v181 offset:0x3200
	ds_read_b64_tr_b16 v[240:241], v181 offset:0x3a00
	s_waitcnt lgkmcnt(0)
	v_mfma_f32_32x32x16_bf16 v[0:15], v[76:79], v[234:237], v[0:15]
	v_mfma_f32_32x32x16_bf16 v[16:31], v[64:67], v[222:225], v[16:31]
	ds_read_b64_tr_b16 v[222:223], v181 offset:0x400
	ds_read_b64_tr_b16 v[224:225], v181 offset:0xc00
	v_mfma_f32_32x32x16_bf16 v[16:31], v[68:71], v[226:229], v[16:31]
	ds_read_b64_tr_b16 v[226:227], v181 offset:0x1400
	ds_read_b64_tr_b16 v[228:229], v181 offset:0x1c00
	v_mfma_f32_32x32x16_bf16 v[16:31], v[72:75], v[230:233], v[16:31]
	ds_read_b64_tr_b16 v[230:231], v181 offset:0x2400
	ds_read_b64_tr_b16 v[232:233], v181 offset:0x2c00
	ds_read_b64_tr_b16 v[234:235], v181 offset:0x3400
	ds_read_b64_tr_b16 v[236:237], v181 offset:0x3c00
	s_waitcnt lgkmcnt(0)
	v_mfma_f32_32x32x16_bf16 v[16:31], v[76:79], v[238:241], v[16:31]
	v_mfma_f32_32x32x16_bf16 v[32:47], v[64:67], v[222:225], v[32:47]
	ds_read_b64_tr_b16 v[222:223], v181 offset:0x600
	ds_read_b64_tr_b16 v[224:225], v181 offset:0xe00
	v_mfma_f32_32x32x16_bf16 v[32:47], v[68:71], v[226:229], v[32:47]
	ds_read_b64_tr_b16 v[226:227], v181 offset:0x1600
	ds_read_b64_tr_b16 v[228:229], v181 offset:0x1e00
	v_mfma_f32_32x32x16_bf16 v[32:47], v[72:75], v[230:233], v[32:47]
	ds_read_b64_tr_b16 v[230:231], v181 offset:0x2600
	ds_read_b64_tr_b16 v[232:233], v181 offset:0x2e00
	ds_read_b64_tr_b16 v[238:239], v181 offset:0x3600
	ds_read_b64_tr_b16 v[240:241], v181 offset:0x3e00
	s_waitcnt lgkmcnt(0)
	v_mfma_f32_32x32x16_bf16 v[32:47], v[76:79], v[234:237], v[32:47]
	v_mfma_f32_32x32x16_bf16 v[48:63], v[64:67], v[222:225], v[48:63]
	v_mfma_f32_32x32x16_bf16 v[48:63], v[68:71], v[226:229], v[48:63]
	v_mfma_f32_32x32x16_bf16 v[48:63], v[72:75], v[230:233], v[48:63]
	v_mfma_f32_32x32x16_bf16 v[48:63], v[76:79], v[238:241], v[48:63]
	v_mov_b64 v[74:75], v[100:101]
	v_mov_b64 v[76:77], v[98:99]
	v_mov_b64 v[78:79], v[96:97]
	v_exp_f32_e32 v173, v76
	v_exp_f32_e32 v169, v78
	v_exp_f32_e32 v171, v79
	v_exp_f32_e32 v175, v77
	v_exp_f32_e32 v177, v74
	v_mov_b64 v[64:65], v[110:111]
	v_mov_b64 v[66:67], v[108:109]
	v_mov_b64 v[68:69], v[106:107]
	v_mov_b64 v[70:71], v[104:105]
	v_mov_b64 v[72:73], v[102:103]
	v_exp_f32_e32 v188, v75
	v_exp_f32_e32 v189, v72
	v_exp_f32_e32 v222, v73
	v_exp_f32_e32 v223, v70
	v_exp_f32_e32 v224, v71
	v_exp_f32_e32 v225, v68
	v_exp_f32_e32 v226, v69
	v_exp_f32_e32 v227, v66
	v_exp_f32_e32 v228, v67
	v_exp_f32_e32 v229, v64
	v_exp_f32_e32 v230, v65
	s_barrier
	s_waitcnt vmcnt(0)
	s_waitcnt vmcnt(3)
	ds_write_b128 v194, v[206:209]
	s_waitcnt vmcnt(1)
	ds_write_b128 v195, v[214:217]
	ds_write_b128 v196, v[210:213] offset:32768
	s_waitcnt vmcnt(0)
	ds_write_b128 v197, v[218:221] offset:32768
	s_waitcnt lgkmcnt(0)
	s_barrier
; #define SBAR() __builtin_amdgcn_sched_barrier(0)
; __device__ __forceinline__ void expA(f32x16& p0, const float negb) { p0 = p0 + negb; for (int r = 0; r < 16; ++r) p0[r] = __builtin_amdgcn_exp2f(p0[r]); }
; #define SLOAD(i, k0) do { const unsigned a_ = (unsigned)(k0) * (unsigned)LDK + so0; sr_[i].vs0 = ld8(Kh + (a_ + 256u)); sr_[i].vs1 = ld8(Kh + (a_ + 32u * LDK + 256u)); \
;     sr_[i].ks0 = ld8(Kh + a_); sr_[i].ks1 = ld8(Kh + (a_ + 32u * LDK)); } while (0)
; __device__ __forceinline__ void finishSM(f32x16& p0, f32x16& p1, const float negb, float& l_reg, bf16x8& pa0, bf16x8& pa1, bf16x8& pa2, bf16x8& pa3) {
;   p1 = p1 + negb; for (int r = 0; r < 16; ++r) p1[r] = __builtin_amdgcn_exp2f(p1[r]);
;   float ps = 0; for (int r = 0; r < 16; ++r) ps += p0[r]; for (int r = 0; r < 16; ++r) ps += p1[r];
;   l_reg += ps;
;     ...
;   PK4(p0, 0, pa0); PK4(p0, 8, pa1); PK4(p1, 0, pa2); PK4(p1, 8, pa3);
;     ...
; }
; __device__ __forceinline__ void qkt(f32x16& p0, f32x16& p1, const bf16* Ks, const bf16x8* qr, int r32, int hi) {
;   p0 = f32x16{}; p1 = f32x16{};
;   for (int d0 = 0; d0 < 8; ++d0) { int cb = (d0 * 16 + hi * 8) * 2;
;     bf16x8 b0 = *reinterpret_cast<const bf16x8*>((const char*)Ks + KSWZ(r32, cb));
;     bf16x8 b1 = *reinterpret_cast<const bf16x8*>((const char*)Ks + KSWZ(32 + r32, cb));
;     p0 = __builtin_amdgcn_mfma_f32_32x32x16_bf16(b0, qr[d0], p0, 0, 0, 0);
;     p1 = __builtin_amdgcn_mfma_f32_32x32x16_bf16(b1, qr[d0], p1, 0, 0, 0); }
; __device__ __forceinline__ void attn_dense_body(const bf16* __restrict__ Qb, const bf16* __restrict__ Kh, const bf16* __restrict__ Vh,
;                                                 bf16* __restrict__ Ob, int seq, char* lds, const float negb) {
;     ...
;     SBAR(); qkt(pA0, pA1, K_lds, qr, r32, hi);
;     finishSM(pB0, pB1, negb, l_reg, pa0, pa1, pa2, pa3); SBAR();
;     SLOAD(SE, (j + 2) * KVBLK); SBAR();
;     pv_d0(o, vb0 + (int)SHM_V, pa0, pa1, pa2, pa3); SBAR(); expA(pA0, negb); SBAR();
	ds_read_b128 v[64:67], v198 offset:32768
	ds_read_b128 v[68:71], v198 offset:40960
	ds_read_b128 v[206:209], v199 offset:32768
	ds_read_b128 v[210:213], v199 offset:40960
	s_waitcnt lgkmcnt(3)
	v_mfma_f32_32x32x16_bf16 v[96:111], v[64:67], v[140:143], 0
	v_exp_f32_e32 v214, v88
	v_exp_f32_e32 v215, v89
	v_exp_f32_e32 v216, v90
	s_waitcnt lgkmcnt(2)
	v_mfma_f32_32x32x16_bf16 v[64:79], v[68:71], v[140:143], 0
	v_exp_f32_e32 v217, v91
	v_exp_f32_e32 v218, v92
	v_exp_f32_e32 v219, v93
	v_exp_f32_e32 v220, v94
	v_exp_f32_e32 v95, v95
	s_waitcnt lgkmcnt(1)
	v_mfma_f32_32x32x16_bf16 v[96:111], v[206:209], v[136:139], v[96:111]
	s_waitcnt lgkmcnt(0)
	v_mfma_f32_32x32x16_bf16 v[64:79], v[210:213], v[136:139], v[64:79]
	ds_read_b128 v[206:209], v200 offset:32768
	ds_read_b128 v[210:213], v200 offset:40960
	s_waitcnt lgkmcnt(1)
	v_mfma_f32_32x32x16_bf16 v[96:111], v[206:209], v[132:135], v[96:111]
	s_waitcnt lgkmcnt(0)
	v_mfma_f32_32x32x16_bf16 v[64:79], v[210:213], v[132:135], v[64:79]
	ds_read_b128 v[206:209], v201 offset:32768
	ds_read_b128 v[210:213], v201 offset:40960
	s_waitcnt lgkmcnt(1)
	v_mfma_f32_32x32x16_bf16 v[96:111], v[206:209], v[128:131], v[96:111]
	s_waitcnt lgkmcnt(0)
	v_mfma_f32_32x32x16_bf16 v[64:79], v[210:213], v[128:131], v[64:79]
	ds_read_b128 v[206:209], v202 offset:32768
	ds_read_b128 v[210:213], v202 offset:40960
	s_waitcnt lgkmcnt(1)
	v_mfma_f32_32x32x16_bf16 v[96:111], v[206:209], v[124:127], v[96:111]
	s_waitcnt lgkmcnt(0)
	v_mfma_f32_32x32x16_bf16 v[64:79], v[210:213], v[124:127], v[64:79]
	ds_read_b128 v[206:209], v203 offset:32768
	ds_read_b128 v[210:213], v203 offset:40960
	s_waitcnt lgkmcnt(1)
	v_mfma_f32_32x32x16_bf16 v[96:111], v[206:209], v[120:123], v[96:111]
	s_waitcnt lgkmcnt(0)
	v_mfma_f32_32x32x16_bf16 v[64:79], v[210:213], v[120:123], v[64:79]
	ds_read_b128 v[206:209], v204 offset:32768
	ds_read_b128 v[210:213], v204 offset:40960
	s_waitcnt lgkmcnt(1)
	v_mfma_f32_32x32x16_bf16 v[96:111], v[206:209], v[116:119], v[96:111]
	s_waitcnt lgkmcnt(0)
	v_mfma_f32_32x32x16_bf16 v[64:79], v[210:213], v[116:119], v[64:79]
	ds_read_b128 v[206:209], v205 offset:32768
	ds_read_b128 v[210:213], v205 offset:40960
	s_waitcnt lgkmcnt(1)
	v_mfma_f32_32x32x16_bf16 v[96:111], v[206:209], v[112:115], v[96:111]
	v_exp_f32_e32 v206, v80
	v_add_f32_e32 v80, 0, v169
	v_add_f32_e32 v80, v171, v80
	v_add_f32_e32 v80, v173, v80
	v_add_f32_e32 v80, v175, v80
	v_add_f32_e32 v80, v177, v80
	v_add_f32_e32 v80, v188, v80
	v_add_f32_e32 v80, v189, v80
	v_add_f32_e32 v80, v222, v80
	v_add_f32_e32 v80, v223, v80
	v_add_f32_e32 v80, v224, v80
	v_add_f32_e32 v80, v225, v80
	v_add_f32_e32 v80, v226, v80
	v_add_f32_e32 v80, v227, v80
	v_exp_f32_e32 v207, v81
	v_add_f32_e32 v80, v228, v80
	v_exp_f32_e32 v208, v82
	v_add_f32_e32 v80, v229, v80
	v_exp_f32_e32 v209, v83
	v_add_f32_e32 v80, v230, v80
	s_waitcnt lgkmcnt(0)
	v_mfma_f32_32x32x16_bf16 v[64:79], v[210:213], v[112:115], v[64:79]
	v_exp_f32_e32 v210, v84
	v_add_f32_e32 v80, v206, v80
	v_exp_f32_e32 v211, v85
	v_add_f32_e32 v80, v207, v80
	v_exp_f32_e32 v212, v86
	v_add_f32_e32 v80, v208, v80
	v_exp_f32_e32 v213, v87
	v_add_f32_e32 v80, v209, v80
	v_add_f32_e32 v80, v210, v80
	v_add_f32_e32 v80, v211, v80
	v_add_f32_e32 v80, v212, v80
	v_add_f32_e32 v80, v213, v80
	v_add_f32_e32 v80, v214, v80
	v_add_f32_e32 v80, v215, v80
	v_add_f32_e32 v80, v216, v80
	v_add_f32_e32 v80, v217, v80
	v_add_f32_e32 v80, v218, v80
	v_add_f32_e32 v80, v219, v80
	v_add_f32_e32 v80, v220, v80
	v_add_f32_e32 v80, v95, v80
	v_add_f32_e32 v167, v167, v80
	v_cvt_pk_bf16_f32 v80, v169, v171
	v_cvt_pk_bf16_f32 v81, v173, v175
	v_cvt_pk_bf16_f32 v82, v177, v188
	v_cvt_pk_bf16_f32 v83, v189, v222
	v_cvt_pk_bf16_f32 v84, v223, v224
	v_cvt_pk_bf16_f32 v85, v225, v226
	v_cvt_pk_bf16_f32 v86, v227, v228
	v_cvt_pk_bf16_f32 v87, v229, v230
	v_cvt_pk_bf16_f32 v88, v206, v207
	v_cvt_pk_bf16_f32 v89, v208, v209
	v_cvt_pk_bf16_f32 v90, v210, v211
	v_cvt_pk_bf16_f32 v91, v212, v213
	v_cvt_pk_bf16_f32 v92, v214, v215
	v_cvt_pk_bf16_f32 v93, v216, v217
	v_cvt_pk_bf16_f32 v94, v218, v219
	v_cvt_pk_bf16_f32 v95, v220, v95
	s_nop 0
	v_permlane32_swap_b32_e32 v80, v82
	v_permlane32_swap_b32_e32 v81, v83
	v_permlane32_swap_b32_e32 v84, v86
	v_permlane32_swap_b32_e32 v85, v87
	v_permlane32_swap_b32_e32 v88, v90
	v_permlane32_swap_b32_e32 v89, v91
	v_permlane32_swap_b32_e32 v92, v94
	v_permlane32_swap_b32_e32 v93, v95
	v_add_u32_e32 v210, 0xc100, v148
	v_mov_b32_e32 v211, v149
	v_lshl_add_u64 v[206:207], v[148:149], 1, s[60:61]
	v_add_u32_e32 v208, 0xc000, v148
	v_lshl_add_u64 v[210:211], v[210:211], 1, s[62:63]
	v_mov_b32_e32 v209, v149
	global_load_dwordx4 v[218:221], v[206:207], off offset:2560
	global_load_dwordx4 v[222:225], v[206:207], off offset:2048
	v_lshl_add_u64 v[206:207], v[208:209], 1, s[62:63]
	global_load_dwordx4 v[226:229], v[210:211], off
	global_load_dwordx4 v[230:233], v[206:207], off
	ds_read_b64_tr_b16 v[206:207], v191 offset:0
	ds_read_b64_tr_b16 v[208:209], v191 offset:0x800
	ds_read_b64_tr_b16 v[210:211], v191 offset:0x1000
	ds_read_b64_tr_b16 v[212:213], v191 offset:0x1800
	ds_read_b64_tr_b16 v[214:215], v191 offset:0x2000
	ds_read_b64_tr_b16 v[216:217], v191 offset:0x2800
	ds_read_b64_tr_b16 v[234:235], v191 offset:0x3000
	ds_read_b64_tr_b16 v[236:237], v191 offset:0x3800
	s_waitcnt lgkmcnt(0)
	s_nop 0
	v_mfma_f32_32x32x16_bf16 v[0:15], v[80:83], v[206:209], v[0:15]
	ds_read_b64_tr_b16 v[206:207], v191 offset:0x200
	ds_read_b64_tr_b16 v[208:209], v191 offset:0xa00
	v_mfma_f32_32x32x16_bf16 v[0:15], v[84:87], v[210:213], v[0:15]
	ds_read_b64_tr_b16 v[210:211], v191 offset:0x1200
	ds_read_b64_tr_b16 v[212:213], v191 offset:0x1a00
	v_mfma_f32_32x32x16_bf16 v[0:15], v[88:91], v[214:217], v[0:15]
	ds_read_b64_tr_b16 v[214:215], v191 offset:0x2200
	ds_read_b64_tr_b16 v[216:217], v191 offset:0x2a00
	ds_read_b64_tr_b16 v[238:239], v191 offset:0x3200
	ds_read_b64_tr_b16 v[240:241], v191 offset:0x3a00
	s_waitcnt lgkmcnt(0)
; #define SBAR() __builtin_amdgcn_sched_barrier(0)
; __device__ __forceinline__ void expA(f32x16& p0, const float negb) { p0 = p0 + negb; for (int r = 0; r < 16; ++r) p0[r] = __builtin_amdgcn_exp2f(p0[r]); }
; #define SWRITE(b, i) do { *(bf16x8*)((char*)V_lds + (b) * SHM_V + vst0) = sr_[i].vs0;          \
;     *(bf16x8*)((char*)V_lds + (b) * SHM_V + vst1) = sr_[i].vs1; int kc = sc * 2;               \
;     *(bf16x8*)((char*)K_lds + (b) * SHM_K + KSWZ(sr, kc)) = sr_[i].ks0;                       \
;     *(bf16x8*)((char*)K_lds + (b) * SHM_K + KSWZ(32 + sr, kc)) = sr_[i].ks1; } while (0)
; #define SWAIT() asm volatile("s_waitcnt vmcnt(0)" ::: "memory")
; template <int D0> __device__ __forceinline__ void pv_one(f32x16& od, int vb, bf16x8 pa0, bf16x8 pa1, bf16x8 pa2, bf16x8 pa3) {
;   const s16x4 l0 = tr_read<v_rd_off(D0, 0, 0)>(vb), h0 = tr_read<v_rd_off(D0, 0, 1)>(vb), l1 = tr_read<v_rd_off(D0, 1, 0)>(vb), h1 = tr_read<v_rd_off(D0, 1, 1)>(vb);
;   const s16x4 l2 = tr_read<v_rd_off(D0, 2, 0)>(vb), h2 = tr_read<v_rd_off(D0, 2, 1)>(vb), l3 = tr_read<v_rd_off(D0, 3, 0)>(vb), h3 = tr_read<v_rd_off(D0, 3, 1)>(vb);
;   asm volatile("s_waitcnt lgkmcnt(0)" ::: "memory"); SBAR();
;     ...
;   od = __builtin_amdgcn_mfma_f32_32x32x16_bf16(pa0, PK(l0, h0), od, 0, 0, 0);
;   od = __builtin_amdgcn_mfma_f32_32x32x16_bf16(pa1, PK(l1, h1), od, 0, 0, 0);
;   od = __builtin_amdgcn_mfma_f32_32x32x16_bf16(pa2, PK(l2, h2), od, 0, 0, 0);
;   od = __builtin_amdgcn_mfma_f32_32x32x16_bf16(pa3, PK(l3, h3), od, 0, 0, 0);
;     ...
; }
; __device__ __forceinline__ void pv_d0(f32x16* o, int vb, bf16x8 pa0, bf16x8 pa1, bf16x8 pa2, bf16x8 pa3) {
;   pv_one<0>(o[0], vb, pa0, pa1, pa2, pa3); pv_one<1>(o[1], vb, pa0, pa1, pa2, pa3); pv_one<2>(o[2], vb, pa0, pa1, pa2, pa3); pv_one<3>(o[3], vb, pa0, pa1, pa2, pa3);
; __device__ __forceinline__ void attn_dense_body(const bf16* __restrict__ Qb, const bf16* __restrict__ Kh, const bf16* __restrict__ Vh,
;                                                 bf16* __restrict__ Ob, int seq, char* lds, const float negb) {
;     ...
;     pv_d0(o, vb0 + (int)SHM_V, pa0, pa1, pa2, pa3); SBAR(); expA(pA0, negb); SBAR();
;     __syncthreads(); SWAIT(); SWRITE(1, SO); SBAR();
;     __syncthreads();
;   }
;   SBAR(); qkt(pB0, pB1, (bf16*)((char*)K_lds + SHM_K), qr, r32, hi);
;   finishSM(pA0, pA1, negb, l_reg, pa0, pa1, pa2, pa3); SBAR();
	v_mfma_f32_32x32x16_bf16 v[0:15], v[92:95], v[234:237], v[0:15]
	v_mfma_f32_32x32x16_bf16 v[16:31], v[80:83], v[206:209], v[16:31]
	ds_read_b64_tr_b16 v[206:207], v191 offset:0x400
	ds_read_b64_tr_b16 v[208:209], v191 offset:0xc00
	v_mfma_f32_32x32x16_bf16 v[16:31], v[84:87], v[210:213], v[16:31]
	ds_read_b64_tr_b16 v[210:211], v191 offset:0x1400
	ds_read_b64_tr_b16 v[212:213], v191 offset:0x1c00
	v_mfma_f32_32x32x16_bf16 v[16:31], v[88:91], v[214:217], v[16:31]
	ds_read_b64_tr_b16 v[214:215], v191 offset:0x2400
	ds_read_b64_tr_b16 v[216:217], v191 offset:0x2c00
	ds_read_b64_tr_b16 v[234:235], v191 offset:0x3400
	ds_read_b64_tr_b16 v[236:237], v191 offset:0x3c00
	s_waitcnt lgkmcnt(0)
	v_mfma_f32_32x32x16_bf16 v[16:31], v[92:95], v[238:241], v[16:31]
	v_mfma_f32_32x32x16_bf16 v[32:47], v[80:83], v[206:209], v[32:47]
	ds_read_b64_tr_b16 v[206:207], v191 offset:0x600
	ds_read_b64_tr_b16 v[208:209], v191 offset:0xe00
	v_mfma_f32_32x32x16_bf16 v[32:47], v[84:87], v[210:213], v[32:47]
	ds_read_b64_tr_b16 v[210:211], v191 offset:0x1600
	ds_read_b64_tr_b16 v[212:213], v191 offset:0x1e00
	v_mfma_f32_32x32x16_bf16 v[32:47], v[88:91], v[214:217], v[32:47]
	ds_read_b64_tr_b16 v[214:215], v191 offset:0x2600
	ds_read_b64_tr_b16 v[216:217], v191 offset:0x2e00
	ds_read_b64_tr_b16 v[238:239], v191 offset:0x3600
	ds_read_b64_tr_b16 v[240:241], v191 offset:0x3e00
	s_waitcnt lgkmcnt(0)
	v_mfma_f32_32x32x16_bf16 v[32:47], v[92:95], v[234:237], v[32:47]
	v_mfma_f32_32x32x16_bf16 v[48:63], v[80:83], v[206:209], v[48:63]
	v_mfma_f32_32x32x16_bf16 v[48:63], v[84:87], v[210:213], v[48:63]
	v_mfma_f32_32x32x16_bf16 v[48:63], v[88:91], v[214:217], v[48:63]
	v_mfma_f32_32x32x16_bf16 v[48:63], v[92:95], v[238:241], v[48:63]
	v_mov_b64 v[80:81], v[110:111]
	v_mov_b64 v[82:83], v[108:109]
	v_mov_b64 v[84:85], v[106:107]
	v_mov_b64 v[86:87], v[104:105]
	v_mov_b64 v[88:89], v[102:103]
	v_mov_b64 v[90:91], v[100:101]
	v_mov_b64 v[92:93], v[98:99]
	v_mov_b64 v[94:95], v[96:97]
	v_exp_f32_e32 v212, v92
	v_exp_f32_e32 v214, v94
	v_exp_f32_e32 v216, v95
	v_exp_f32_e32 v215, v93
	v_exp_f32_e32 v211, v90
	v_exp_f32_e32 v213, v91
	v_exp_f32_e32 v209, v88
	v_exp_f32_e32 v210, v89
	v_exp_f32_e32 v206, v86
	v_exp_f32_e32 v208, v87
	v_exp_f32_e32 v177, v84
	v_exp_f32_e32 v207, v85
	v_exp_f32_e32 v171, v82
	v_exp_f32_e32 v175, v83
	v_exp_f32_e32 v169, v80
	v_exp_f32_e32 v173, v81
	s_barrier
	s_waitcnt vmcnt(0)
	s_waitcnt vmcnt(3)
	ds_write_b128 v194, v[218:221] offset:16384
	s_waitcnt vmcnt(1)
	ds_write_b128 v195, v[226:229] offset:16384
	ds_write_b128 v196, v[222:225] offset:49152
	s_waitcnt vmcnt(0)
	ds_write_b128 v197, v[230:233] offset:49152
	s_add_i32 s64, s64, 2
	v_add_u32_e32 v148, 0x30000, v148
	s_cmp_ge_u32 s64, s82
	v_lshl_add_u64 v[178:179], v[178:179], 0, s[6:7]
	s_waitcnt lgkmcnt(0)
	s_barrier
	s_cbranch_scc0 .LBB0_516
	ds_read_b128 v[80:83], v198 offset:49152
	ds_read_b128 v[84:87], v198 offset:57344
	s_waitcnt lgkmcnt(1)
	v_mfma_f32_32x32x16_bf16 v[96:111], v[80:83], v[140:143], 0
	s_nop 0
	v_exp_f32_e32 v79, v79
	s_waitcnt lgkmcnt(0)
	v_mfma_f32_32x32x16_bf16 v[80:95], v[84:87], v[140:143], 0
	ds_read_b128 v[140:143], v199 offset:49152
	ds_read_b128 v[218:221], v199 offset:57344
	s_waitcnt lgkmcnt(1)
	v_mfma_f32_32x32x16_bf16 v[96:111], v[140:143], v[136:139], v[96:111]
	s_waitcnt lgkmcnt(0)
	v_mfma_f32_32x32x16_bf16 v[80:95], v[218:221], v[136:139], v[80:95]
	ds_read_b128 v[136:139], v200 offset:49152
	ds_read_b128 v[140:143], v200 offset:57344
	s_waitcnt lgkmcnt(1)
	v_mfma_f32_32x32x16_bf16 v[96:111], v[136:139], v[132:135], v[96:111]
	s_waitcnt lgkmcnt(0)
	v_mfma_f32_32x32x16_bf16 v[80:95], v[140:143], v[132:135], v[80:95]
	ds_read_b128 v[132:135], v201 offset:49152
	ds_read_b128 v[136:139], v201 offset:57344
	s_waitcnt lgkmcnt(1)
	v_mfma_f32_32x32x16_bf16 v[96:111], v[132:135], v[128:131], v[96:111]
	s_waitcnt lgkmcnt(0)
	v_mfma_f32_32x32x16_bf16 v[80:95], v[136:139], v[128:131], v[80:95]
	ds_read_b128 v[128:131], v202 offset:49152
	ds_read_b128 v[132:135], v202 offset:57344
	s_waitcnt lgkmcnt(1)
	v_mfma_f32_32x32x16_bf16 v[96:111], v[128:131], v[124:127], v[96:111]
	s_waitcnt lgkmcnt(0)
	v_mfma_f32_32x32x16_bf16 v[80:95], v[132:135], v[124:127], v[80:95]
	ds_read_b128 v[124:127], v203 offset:49152
	ds_read_b128 v[128:131], v203 offset:57344
	s_waitcnt lgkmcnt(1)
	v_mfma_f32_32x32x16_bf16 v[96:111], v[124:127], v[120:123], v[96:111]
	s_waitcnt lgkmcnt(0)
	v_mfma_f32_32x32x16_bf16 v[80:95], v[128:131], v[120:123], v[80:95]
	ds_read_b128 v[120:123], v204 offset:49152
	ds_read_b128 v[124:127], v204 offset:57344
	s_waitcnt lgkmcnt(1)
	v_mfma_f32_32x32x16_bf16 v[96:111], v[120:123], v[116:119], v[96:111]
	s_waitcnt lgkmcnt(0)
	v_mfma_f32_32x32x16_bf16 v[80:95], v[124:127], v[116:119], v[80:95]
	ds_read_b128 v[116:119], v205 offset:49152
	ds_read_b128 v[120:123], v205 offset:57344
	v_exp_f32_e32 v124, v76
	v_exp_f32_e32 v125, v77
	v_exp_f32_e32 v126, v78
	s_waitcnt lgkmcnt(1)
	v_mfma_f32_32x32x16_bf16 v[96:111], v[116:119], v[112:115], v[96:111]
	v_exp_f32_e32 v116, v68
	v_exp_f32_e32 v117, v69
	v_exp_f32_e32 v118, v70
	v_exp_f32_e32 v119, v71
	s_waitcnt lgkmcnt(0)
; __device__ __forceinline__ void finishSM(f32x16& p0, f32x16& p1, const float negb, float& l_reg, bf16x8& pa0, bf16x8& pa1, bf16x8& pa2, bf16x8& pa3) {
;   p1 = p1 + negb; for (int r = 0; r < 16; ++r) p1[r] = __builtin_amdgcn_exp2f(p1[r]);
;   float ps = 0; for (int r = 0; r < 16; ++r) ps += p0[r]; for (int r = 0; r < 16; ++r) ps += p1[r];
;   l_reg += ps;
;     ...
;   PK4(p0, 0, pa0); PK4(p0, 8, pa1); PK4(p1, 0, pa2); PK4(p1, 8, pa3);
;     ...
; }
; __device__ __forceinline__ void qkt(f32x16& p0, f32x16& p1, const bf16* Ks, const bf16x8* qr, int r32, int hi) {
;   p0 = f32x16{}; p1 = f32x16{};
;   for (int d0 = 0; d0 < 8; ++d0) { int cb = (d0 * 16 + hi * 8) * 2;
;     bf16x8 b0 = *reinterpret_cast<const bf16x8*>((const char*)Ks + KSWZ(r32, cb));
;     bf16x8 b1 = *reinterpret_cast<const bf16x8*>((const char*)Ks + KSWZ(32 + r32, cb));
;     p0 = __builtin_amdgcn_mfma_f32_32x32x16_bf16(b0, qr[d0], p0, 0, 0, 0);
;     p1 = __builtin_amdgcn_mfma_f32_32x32x16_bf16(b1, qr[d0], p1, 0, 0, 0); }
; }
; __device__ __forceinline__ int v_st(int k, int c) { const int kk = (k & ~0xC) | ((k & 4) << 1) | ((k & 8) >> 1); return ((kk >> 3) * 4 + (c >> 5)) * 512 + ((kk & 7) * 32 + (c & 31)) * 2; }
; __device__ __forceinline__ int v_rd_base(int lane) { return ((lane & 3) << 3) | (((lane >> 2) & 3) << 6) | (((lane >> 4) & 1) << 5) | (((lane >> 5) & 1) << 8); }
; template <int OFF> __device__ __forceinline__ s16x4 tr_read(int vb) {
;   s16x4 r; asm volatile("ds_read_b64_tr_b16 %0, %1 offset:%2" : "=&v"(r) : "v"(vb), "i"(OFF) : "memory"); return r;
; }
; template <int D0> __device__ __forceinline__ void pv_one(f32x16& od, int vb, bf16x8 pa0, bf16x8 pa1, bf16x8 pa2, bf16x8 pa3) {
;   const s16x4 l0 = tr_read<v_rd_off(D0, 0, 0)>(vb), h0 = tr_read<v_rd_off(D0, 0, 1)>(vb), l1 = tr_read<v_rd_off(D0, 1, 0)>(vb), h1 = tr_read<v_rd_off(D0, 1, 1)>(vb);
;   const s16x4 l2 = tr_read<v_rd_off(D0, 2, 0)>(vb), h2 = tr_read<v_rd_off(D0, 2, 1)>(vb), l3 = tr_read<v_rd_off(D0, 3, 0)>(vb), h3 = tr_read<v_rd_off(D0, 3, 1)>(vb);
;   asm volatile("s_waitcnt lgkmcnt(0)" ::: "memory"); SBAR();
;     ...
;   od = __builtin_amdgcn_mfma_f32_32x32x16_bf16(pa0, PK(l0, h0), od, 0, 0, 0);
;   od = __builtin_amdgcn_mfma_f32_32x32x16_bf16(pa1, PK(l1, h1), od, 0, 0, 0);
;   od = __builtin_amdgcn_mfma_f32_32x32x16_bf16(pa2, PK(l2, h2), od, 0, 0, 0);
;   od = __builtin_amdgcn_mfma_f32_32x32x16_bf16(pa3, PK(l3, h3), od, 0, 0, 0);
;     ...
; }
	v_mfma_f32_32x32x16_bf16 v[80:95], v[120:123], v[112:115], v[80:95]
	v_exp_f32_e32 v112, v64
	v_add_f32_e32 v64, 0, v214
	v_add_f32_e32 v64, v216, v64
	v_add_f32_e32 v64, v212, v64
	v_add_f32_e32 v64, v215, v64
	v_add_f32_e32 v64, v211, v64
	v_add_f32_e32 v64, v213, v64
	v_add_f32_e32 v64, v209, v64
	v_add_f32_e32 v64, v210, v64
	v_add_f32_e32 v64, v206, v64
	v_add_f32_e32 v64, v208, v64
	v_add_f32_e32 v64, v177, v64
	v_add_f32_e32 v64, v207, v64
	v_add_f32_e32 v64, v171, v64
	v_exp_f32_e32 v113, v65
	v_add_f32_e32 v64, v175, v64
	v_exp_f32_e32 v114, v66
	v_add_f32_e32 v64, v169, v64
	v_exp_f32_e32 v115, v67
	v_add_f32_e32 v64, v173, v64
	v_add_f32_e32 v64, v112, v64
	v_add_f32_e32 v64, v113, v64
	v_add_f32_e32 v64, v114, v64
	v_add_f32_e32 v64, v115, v64
	v_exp_f32_e32 v120, v72
	v_add_f32_e32 v64, v116, v64
	v_exp_f32_e32 v121, v73
	v_add_f32_e32 v64, v117, v64
	v_exp_f32_e32 v122, v74
	v_add_f32_e32 v64, v118, v64
	v_exp_f32_e32 v123, v75
	v_add_f32_e32 v64, v119, v64
	v_add_f32_e32 v64, v120, v64
	v_add_f32_e32 v64, v121, v64
	v_add_f32_e32 v64, v122, v64
	v_add_f32_e32 v64, v123, v64
	v_add_f32_e32 v64, v124, v64
	v_add_f32_e32 v64, v125, v64
	v_add_f32_e32 v64, v126, v64
	v_add_f32_e32 v64, v79, v64
	v_add_f32_e32 v132, v167, v64
	v_cvt_pk_bf16_f32 v64, v214, v216
	v_cvt_pk_bf16_f32 v65, v212, v215
	v_cvt_pk_bf16_f32 v66, v211, v213
	v_cvt_pk_bf16_f32 v67, v209, v210
	v_cvt_pk_bf16_f32 v68, v206, v208
	v_cvt_pk_bf16_f32 v69, v177, v207
	v_cvt_pk_bf16_f32 v70, v171, v175
	v_cvt_pk_bf16_f32 v71, v169, v173
	s_nop 0
	v_permlane32_swap_b32_e32 v64, v66
	v_permlane32_swap_b32_e32 v65, v67
	v_cvt_pk_bf16_f32 v72, v112, v113
	v_cvt_pk_bf16_f32 v73, v114, v115
	v_cvt_pk_bf16_f32 v74, v116, v117
	v_cvt_pk_bf16_f32 v75, v118, v119
	v_cvt_pk_bf16_f32 v76, v120, v121
	v_cvt_pk_bf16_f32 v77, v122, v123
	v_cvt_pk_bf16_f32 v78, v124, v125
	v_cvt_pk_bf16_f32 v79, v126, v79
	v_permlane32_swap_b32_e32 v68, v70
	v_permlane32_swap_b32_e32 v69, v71
	v_permlane32_swap_b32_e32 v72, v74
	v_permlane32_swap_b32_e32 v73, v75
	v_permlane32_swap_b32_e32 v76, v78
	v_permlane32_swap_b32_e32 v77, v79
	ds_read_b64_tr_b16 v[112:113], v181 offset:0
	ds_read_b64_tr_b16 v[114:115], v181 offset:0x800
	ds_read_b64_tr_b16 v[116:117], v181 offset:0x1000
	ds_read_b64_tr_b16 v[118:119], v181 offset:0x1800
	ds_read_b64_tr_b16 v[120:121], v181 offset:0x2000
	ds_read_b64_tr_b16 v[122:123], v181 offset:0x2800
	ds_read_b64_tr_b16 v[124:125], v181 offset:0x3000
	ds_read_b64_tr_b16 v[126:127], v181 offset:0x3800
	s_waitcnt lgkmcnt(0)
	s_nop 0
	v_mfma_f32_32x32x16_bf16 v[0:15], v[64:67], v[112:115], v[0:15]
	ds_read_b64_tr_b16 v[112:113], v181 offset:0x200
	ds_read_b64_tr_b16 v[114:115], v181 offset:0xa00
	v_mfma_f32_32x32x16_bf16 v[0:15], v[68:71], v[116:119], v[0:15]
	ds_read_b64_tr_b16 v[116:117], v181 offset:0x1200
	ds_read_b64_tr_b16 v[118:119], v181 offset:0x1a00
	v_mfma_f32_32x32x16_bf16 v[0:15], v[72:75], v[120:123], v[0:15]
	ds_read_b64_tr_b16 v[120:121], v181 offset:0x2200
	ds_read_b64_tr_b16 v[122:123], v181 offset:0x2a00
	ds_read_b64_tr_b16 v[128:129], v181 offset:0x3200
	ds_read_b64_tr_b16 v[130:131], v181 offset:0x3a00
	s_waitcnt lgkmcnt(0)
	v_mfma_f32_32x32x16_bf16 v[0:15], v[76:79], v[124:127], v[0:15]
	v_mfma_f32_32x32x16_bf16 v[16:31], v[64:67], v[112:115], v[16:31]
	ds_read_b64_tr_b16 v[112:113], v181 offset:0x400
	ds_read_b64_tr_b16 v[114:115], v181 offset:0xc00
	v_mfma_f32_32x32x16_bf16 v[16:31], v[68:71], v[116:119], v[16:31]
	ds_read_b64_tr_b16 v[116:117], v181 offset:0x1400
	ds_read_b64_tr_b16 v[118:119], v181 offset:0x1c00
	v_mfma_f32_32x32x16_bf16 v[16:31], v[72:75], v[120:123], v[16:31]
	ds_read_b64_tr_b16 v[120:121], v181 offset:0x2400
	ds_read_b64_tr_b16 v[122:123], v181 offset:0x2c00
	ds_read_b64_tr_b16 v[124:125], v181 offset:0x3400
	ds_read_b64_tr_b16 v[126:127], v181 offset:0x3c00
	s_waitcnt lgkmcnt(0)
	v_mfma_f32_32x32x16_bf16 v[16:31], v[76:79], v[128:131], v[16:31]
	v_mfma_f32_32x32x16_bf16 v[32:47], v[64:67], v[112:115], v[32:47]
	ds_read_b64_tr_b16 v[112:113], v181 offset:0x600
	ds_read_b64_tr_b16 v[114:115], v181 offset:0xe00
	v_mfma_f32_32x32x16_bf16 v[32:47], v[68:71], v[116:119], v[32:47]
	ds_read_b64_tr_b16 v[116:117], v181 offset:0x1600
	ds_read_b64_tr_b16 v[118:119], v181 offset:0x1e00
	v_mfma_f32_32x32x16_bf16 v[32:47], v[72:75], v[120:123], v[32:47]
	ds_read_b64_tr_b16 v[120:121], v181 offset:0x2600
	ds_read_b64_tr_b16 v[122:123], v181 offset:0x2e00
	ds_read_b64_tr_b16 v[128:129], v181 offset:0x3600
	ds_read_b64_tr_b16 v[130:131], v181 offset:0x3e00
	s_waitcnt lgkmcnt(0)
	v_mfma_f32_32x32x16_bf16 v[32:47], v[76:79], v[124:127], v[32:47]
	v_mfma_f32_32x32x16_bf16 v[48:63], v[64:67], v[112:115], v[48:63]
	v_mov_b64 v[66:67], v[96:97]
	v_mov_b64 v[64:65], v[98:99]
	v_exp_f32_e32 v96, v66
	v_exp_f32_e32 v97, v67
	v_exp_f32_e32 v98, v64
	v_exp_f32_e32 v99, v65
	v_mfma_f32_32x32x16_bf16 v[48:63], v[68:71], v[116:119], v[48:63]
	v_mov_b64 v[64:65], v[94:95]
	v_exp_f32_e32 v100, v100
	v_mov_b64 v[68:69], v[90:91]
	v_exp_f32_e32 v90, v64
	v_add_f32_e32 v64, 0, v96
	v_exp_f32_e32 v101, v101
	v_add_f32_e32 v64, v97, v64
	v_exp_f32_e32 v102, v102
	v_add_f32_e32 v64, v98, v64
	v_exp_f32_e32 v103, v103
	v_mfma_f32_32x32x16_bf16 v[48:63], v[72:75], v[120:123], v[48:63]
	v_add_f32_e32 v64, v99, v64
	v_exp_f32_e32 v104, v104
	v_add_f32_e32 v64, v100, v64
	v_exp_f32_e32 v105, v105
	v_add_f32_e32 v64, v101, v64
	v_exp_f32_e32 v106, v106
	v_add_f32_e32 v64, v102, v64
	v_exp_f32_e32 v107, v107
	v_add_f32_e32 v64, v103, v64
	v_exp_f32_e32 v108, v108
	v_add_f32_e32 v64, v104, v64
	v_exp_f32_e32 v109, v109
	v_add_f32_e32 v64, v105, v64
	v_exp_f32_e32 v110, v110
	v_add_f32_e32 v64, v106, v64
	v_exp_f32_e32 v111, v111
	v_mfma_f32_32x32x16_bf16 v[48:63], v[76:79], v[128:131], v[48:63]
	v_mov_b64 v[78:79], v[80:81]
	v_add_f32_e32 v64, v107, v64
	v_exp_f32_e32 v78, v78
	v_add_f32_e32 v64, v108, v64
	v_mov_b64 v[76:77], v[82:83]
	v_exp_f32_e32 v79, v79
	v_add_f32_e32 v64, v109, v64
	v_exp_f32_e32 v76, v76
	v_add_f32_e32 v64, v110, v64
	v_mov_b64 v[74:75], v[84:85]
	v_exp_f32_e32 v77, v77
	v_add_f32_e32 v64, v111, v64
	v_exp_f32_e32 v80, v74
	v_add_f32_e32 v64, v78, v64
	v_mov_b64 v[72:73], v[86:87]
	v_exp_f32_e32 v81, v75
	v_add_f32_e32 v64, v79, v64
	v_exp_f32_e32 v82, v72
	v_add_f32_e32 v64, v76, v64
	v_mov_b64 v[70:71], v[88:89]
	v_exp_f32_e32 v83, v73
	v_add_f32_e32 v64, v77, v64
	v_exp_f32_e32 v84, v70
	v_add_f32_e32 v64, v80, v64
	v_exp_f32_e32 v85, v71
	v_add_f32_e32 v64, v81, v64
	v_exp_f32_e32 v86, v68
	v_add_f32_e32 v64, v82, v64
	v_mov_b64 v[66:67], v[92:93]
	v_exp_f32_e32 v87, v69
	v_add_f32_e32 v64, v83, v64
	v_exp_f32_e32 v88, v66
	v_add_f32_e32 v64, v84, v64
	v_exp_f32_e32 v89, v67
	v_add_f32_e32 v64, v85, v64
	v_add_f32_e32 v64, v86, v64
	v_exp_f32_e32 v65, v65
	v_add_f32_e32 v64, v87, v64
	v_add_f32_e32 v64, v88, v64
	v_add_f32_e32 v64, v89, v64
	v_add_f32_e32 v64, v90, v64
	v_add_f32_e32 v64, v65, v64
	s_barrier
; #define SBAR() __builtin_amdgcn_sched_barrier(0)
; __device__ __forceinline__ void finishSM(f32x16& p0, f32x16& p1, const float negb, float& l_reg, bf16x8& pa0, bf16x8& pa1, bf16x8& pa2, bf16x8& pa3) {
;   p1 = p1 + negb; for (int r = 0; r < 16; ++r) p1[r] = __builtin_amdgcn_exp2f(p1[r]);
;   float ps = 0; for (int r = 0; r < 16; ++r) ps += p0[r]; for (int r = 0; r < 16; ++r) ps += p1[r];
;   l_reg += ps;
;     ...
;   PK4(p0, 0, pa0); PK4(p0, 8, pa1); PK4(p1, 0, pa2); PK4(p1, 8, pa3);
;     ...
; }
; __device__ __forceinline__ void attn_dense_body(const bf16* __restrict__ Qb, const bf16* __restrict__ Kh, const bf16* __restrict__ Vh,
;                                                 bf16* __restrict__ Ob, int seq, char* lds, const float negb) {
;     ...
;   finishSM(pB0, pB1, negb, l_reg, pa0, pa1, pa2, pa3); SBAR();
;   pv_d0(o, vb0 + (int)SHM_V, pa0, pa1, pa2, pa3);
;   { auto rr = __builtin_amdgcn_permlane32_swap(__float_as_uint(l_reg), __float_as_uint(l_reg), false, false); l_reg = __uint_as_float(rr[0]) + __uint_as_float(rr[1]); }
;   if (hi == 0) li_l[r32] = l_reg; asm volatile("s_waitcnt lgkmcnt(0)" ::: "memory");
	v_add_f32_e32 v64, v132, v64
	v_cvt_pk_bf16_f32 v66, v96, v97
	v_cvt_pk_bf16_f32 v67, v98, v99
	v_cvt_pk_bf16_f32 v68, v100, v101
	v_cvt_pk_bf16_f32 v69, v102, v103
	v_cvt_pk_bf16_f32 v70, v104, v105
	v_cvt_pk_bf16_f32 v71, v106, v107
	v_cvt_pk_bf16_f32 v72, v108, v109
	v_cvt_pk_bf16_f32 v73, v110, v111
	v_cvt_pk_bf16_f32 v74, v78, v79
	v_cvt_pk_bf16_f32 v75, v76, v77
	v_cvt_pk_bf16_f32 v76, v80, v81
	v_cvt_pk_bf16_f32 v77, v82, v83
	v_cvt_pk_bf16_f32 v78, v84, v85
	v_cvt_pk_bf16_f32 v79, v86, v87
	v_cvt_pk_bf16_f32 v80, v88, v89
	v_cvt_pk_bf16_f32 v81, v90, v65
	s_nop 0
	v_permlane32_swap_b32_e32 v66, v68
	v_permlane32_swap_b32_e32 v67, v69
	v_permlane32_swap_b32_e32 v70, v72
	v_permlane32_swap_b32_e32 v71, v73
	v_permlane32_swap_b32_e32 v74, v76
	v_permlane32_swap_b32_e32 v75, v77
	v_permlane32_swap_b32_e32 v78, v80
	v_permlane32_swap_b32_e32 v79, v81
	ds_read_b64_tr_b16 v[82:83], v191 offset:0
	ds_read_b64_tr_b16 v[84:85], v191 offset:0x800
	ds_read_b64_tr_b16 v[86:87], v191 offset:0x1000
	ds_read_b64_tr_b16 v[88:89], v191 offset:0x1800
	ds_read_b64_tr_b16 v[90:91], v191 offset:0x2000
	ds_read_b64_tr_b16 v[92:93], v191 offset:0x2800
	ds_read_b64_tr_b16 v[94:95], v191 offset:0x3000
	ds_read_b64_tr_b16 v[96:97], v191 offset:0x3800
	s_waitcnt lgkmcnt(0)
	s_nop 0
	v_mfma_f32_32x32x16_bf16 v[0:15], v[66:69], v[82:85], v[0:15]
	ds_read_b64_tr_b16 v[82:83], v191 offset:0x200
	ds_read_b64_tr_b16 v[84:85], v191 offset:0xa00
	v_mfma_f32_32x32x16_bf16 v[0:15], v[70:73], v[86:89], v[0:15]
	ds_read_b64_tr_b16 v[86:87], v191 offset:0x1200
	ds_read_b64_tr_b16 v[88:89], v191 offset:0x1a00
	v_mfma_f32_32x32x16_bf16 v[0:15], v[74:77], v[90:93], v[0:15]
	ds_read_b64_tr_b16 v[90:91], v191 offset:0x2200
	ds_read_b64_tr_b16 v[92:93], v191 offset:0x2a00
	ds_read_b64_tr_b16 v[98:99], v191 offset:0x3200
	ds_read_b64_tr_b16 v[100:101], v191 offset:0x3a00
	s_waitcnt lgkmcnt(0)
	v_mfma_f32_32x32x16_bf16 v[0:15], v[78:81], v[94:97], v[0:15]
	v_mfma_f32_32x32x16_bf16 v[16:31], v[66:69], v[82:85], v[16:31]
	ds_read_b64_tr_b16 v[82:83], v191 offset:0x400
	ds_read_b64_tr_b16 v[84:85], v191 offset:0xc00
	v_mfma_f32_32x32x16_bf16 v[16:31], v[70:73], v[86:89], v[16:31]
	ds_read_b64_tr_b16 v[86:87], v191 offset:0x1400
	ds_read_b64_tr_b16 v[88:89], v191 offset:0x1c00
	v_mfma_f32_32x32x16_bf16 v[16:31], v[74:77], v[90:93], v[16:31]
	ds_read_b64_tr_b16 v[90:91], v191 offset:0x2400
	ds_read_b64_tr_b16 v[92:93], v191 offset:0x2c00
	ds_read_b64_tr_b16 v[94:95], v191 offset:0x3400
	ds_read_b64_tr_b16 v[96:97], v191 offset:0x3c00
	s_waitcnt lgkmcnt(0)
	v_mfma_f32_32x32x16_bf16 v[16:31], v[78:81], v[98:101], v[16:31]
	v_mfma_f32_32x32x16_bf16 v[32:47], v[66:69], v[82:85], v[32:47]
	ds_read_b64_tr_b16 v[82:83], v191 offset:0x600
	ds_read_b64_tr_b16 v[84:85], v191 offset:0xe00
	v_mfma_f32_32x32x16_bf16 v[32:47], v[70:73], v[86:89], v[32:47]
	ds_read_b64_tr_b16 v[86:87], v191 offset:0x1600
	ds_read_b64_tr_b16 v[88:89], v191 offset:0x1e00
	v_mfma_f32_32x32x16_bf16 v[32:47], v[74:77], v[90:93], v[32:47]
	ds_read_b64_tr_b16 v[90:91], v191 offset:0x2600
	ds_read_b64_tr_b16 v[92:93], v191 offset:0x2e00
	ds_read_b64_tr_b16 v[98:99], v191 offset:0x3600
	ds_read_b64_tr_b16 v[100:101], v191 offset:0x3e00
	s_waitcnt lgkmcnt(0)
	v_mfma_f32_32x32x16_bf16 v[32:47], v[78:81], v[94:97], v[32:47]
	v_mfma_f32_32x32x16_bf16 v[48:63], v[66:69], v[82:85], v[48:63]
	v_mov_b32_e32 v65, v64
	s_nop 1
	v_permlane32_swap_b32_e32 v64, v65
	v_mfma_f32_32x32x16_bf16 v[48:63], v[70:73], v[86:89], v[48:63]
	v_mfma_f32_32x32x16_bf16 v[48:63], v[74:77], v[90:93], v[48:63]
	v_mfma_f32_32x32x16_bf16 v[48:63], v[78:81], v[98:101], v[48:63]
	s_and_saveexec_b64 s[60:61], s[0:1]
	s_cbranch_execz .LBB0_512
	v_add_f32_e32 v64, v64, v65
	ds_write_b32 v192, v64
	s_branch .LBB0_512
